# swiglu epilogue regenerated (in-place, rcp(rinv2*(1+e)) via pk_fma, 32-bit saddr store offsets) + zero-peel on all three GEMM loops + deferred rstd wait
# speedup vs baseline: 1.0067x; 1.0067x over previous
; #define PG8_STAGE(bufoff, gbase, voff) do { _Pragma("unroll") for (int _i = 0; _i < 2; ++_i) \
;         __builtin_amdgcn_global_load_lds((const unsigned*)((const char*)(gbase) + (voff)[_i]), (LAS unsigned*)(lds + (bufoff) + ldsw + _i * 8192), 16, 0, 0); } while (0)
; template <class Epi>
; __device__ __forceinline__ void gemm_phase(LAS unsigned char* lds, const Gemm g, const Order& S, const Epi& E, const int tid) {
;     const int wid = __builtin_amdgcn_readfirstlane(tid >> 6), lane = tid & 63, wr = wid >> 2, wc = wid & 3, fr = lane & 15, fq = lane >> 4;
;     const int K = g.K, nt = K / BK;
;     unsigned voffA[2], voffB[2];
; #pragma unroll
;     for (int i = 0; i < 2; ++i) { int R, C; stage_rc(tid * 16 + i * 8192, R, C); const int Rb = (R & ~31) + perm32(R & 31);
;         voffA[i] = (unsigned)(R * K + C) * 2u; voffB[i] = (unsigned)(Rb * K + C) * 2u; }
;     const size_t kstep = (size_t)(BK * 2);
;     const size_t hstep = (size_t)HALF * K * 2;
;     const size_t tstep = 2 * hstep;
;     const unsigned ldsw = (unsigned)wid * 1024u;
;     const int aoff = lds_byte(wr * 64 + fr, fq * 8), boff = lds_byte(wc * 32 + fr, fq * 8);
;     ...
;     Unit cur, nxt; int ui = 0;
;     if (!S.next(0, cur)) return;
;     float rp0 = 0.f, rp1 = 0.f;
;     if constexpr (Epi::NEEDS_RSTD) { const int rr = cur.pm * BM + wr * 64 + fr + 16 * fq; rp0 = row_rstd(E.ssq, rr); rp1 = row_rstd(E.ssq, rr + HALF); }
;     f32x4 acc[2][2][4][2];
; #pragma unroll
;     for (int a = 0; a < 2; ++a)
; #pragma unroll
;         for (int b = 0; b < 2; ++b)
; #pragma unroll
;             for (int m = 0; m < 4; ++m)
; #pragma unroll
;                 for (int n = 0; n < 2; ++n) { double zl, zh; asm volatile("v_mov_b64 %0, 0\n\tv_mov_b64 %1, 0" : "=v"(zl), "=v"(zh)); d64x2 zz = {zl, zh}; acc[a][b][m][n] = __builtin_bit_cast(f32x4, zz); }
;     bf16x8 At[4][2], B0[2][2], B1[2][2];
;     const char* cA = (const char*)g.A + (size_t)cur.pm * tstep; const char* cB = (const char*)g.Bt + (size_t)cur.pn * tstep;
;     PG8_STAGE(PG8_SB(0, 0), cB, voffB); PG8_STAGE(PG8_SB(0, 1), cB + hstep, voffB); PG8_STAGE(PG8_SA(0, 0), cA, voffA); PG8_STAGE(PG8_SA(0, 1), cA + hstep, voffA);
;     if (wr == 1) PG8_BAR;
;     PG8_WAIT_V(2); PG8_BAR;
;     PG8_STAGE(PG8_SB(1, 0), cB + kstep, voffB); PG8_STAGE(PG8_SA(1, 0), cA + kstep, voffA); PG8_STAGE(PG8_SB(1, 1), cB + hstep + kstep, voffB);
;     PG8_WAIT_V(6); PG8_BAR;
.LBB0_88:
	s_andn2_b64 vcc, exec, s[4:5]
	s_cbranch_vccnz .LBB0_174
	v_bfe_i32 v3, v218, 27, 1
	v_lshlrev_b32_e32 v2, 4, v218
	v_lshrrev_b32_e32 v3, 22, v3
	v_add_u32_e32 v3, v2, v3
	v_and_b32_e32 v3, 0xfffffc00, v3
	v_sub_u32_e32 v3, v2, v3
	v_lshrrev_b32_e32 v4, 4, v3
	v_ashrrev_i32_e32 v0, 31, v218
	v_bitop3_b32 v3, v4, v3, 32 bitop3:0x6c
	v_lshrrev_b32_e32 v0, 26, v0
	v_ashrrev_i32_e32 v5, 31, v3
	v_add_u32_e32 v0, v218, v0
	v_lshrrev_b32_e32 v5, 26, v5
	v_ashrrev_i32_e32 v0, 6, v0
	v_add_u32_e32 v5, v3, v5
	v_lshlrev_b32_e32 v4, 3, v0
	v_ashrrev_i32_e32 v156, 6, v5
	v_and_b32_e32 v5, 0xc0, v5
	s_and_b64 s[4:5], s[26:27], exec
	s_mov_b32 s3, 0x4200000
	v_and_b32_e32 v4, -16, v4
	v_sub_u32_e32 v3, v3, v5
	s_cselect_b32 s3, s3, 0x4780000
	v_add_u32_e32 v4, v156, v4
	v_ashrrev_i16_sdwa v3, v183, sext(v3) dst_sel:DWORD dst_unused:UNUSED_PAD src0_sel:DWORD src1_sel:BYTE_0
	s_add_u32 s49, s18, s3
	v_lshlrev_b32_e32 v6, 5, v0
	v_bfe_i32 v157, v3, 0, 16
	v_lshlrev_b32_e32 v3, 1, v4
	v_lshrrev_b32_e32 v5, 2, v4
	v_and_b32_e32 v7, 3, v156
	s_mov_b32 s3, 0x1fffe0
	v_and_b32_e32 v6, 32, v6
	v_and_b32_e32 v3, 24, v3
	v_and_b32_e32 v5, 4, v5
	v_and_or_b32 v7, v4, s3, v7
	v_or3_b32 v3, v7, v5, v3
	v_add_lshl_u32 v5, v6, v157, 1
	v_add_u32_e32 v2, 0x2000, v2
	v_lshl_add_u32 v144, v3, 11, v5
	v_ashrrev_i32_e32 v3, 31, v2
	v_lshrrev_b32_e32 v3, 22, v3
	v_add_u32_e32 v3, v2, v3
	v_ashrrev_i32_e32 v158, 10, v3
	v_mul_i32_i24_e32 v3, 0x400, v158
	v_sub_u32_e32 v2, v2, v3
	v_lshrrev_b32_e32 v3, 4, v2
	v_bitop3_b32 v2, v3, v2, 32 bitop3:0x6c
	v_lshl_add_u32 v142, v4, 11, v5
	v_ashrrev_i32_e32 v4, 31, v2
	v_lshrrev_b32_e32 v4, 26, v4
	v_add_u32_e32 v4, v2, v4
	v_lshlrev_b32_e32 v3, 3, v158
	v_ashrrev_i32_e32 v159, 6, v4
	v_and_b32_e32 v4, 0xc0, v4
	v_and_b32_e32 v3, -16, v3
	v_sub_u32_e32 v2, v2, v4
	v_writelane_b32 v255, s50, 51
	v_add_u32_e32 v3, v159, v3
	v_ashrrev_i16_sdwa v2, v183, sext(v2) dst_sel:DWORD dst_unused:UNUSED_PAD src0_sel:DWORD src1_sel:BYTE_0
	v_writelane_b32 v255, s51, 52
	s_addc_u32 s50, s19, 0
	v_lshlrev_b32_e32 v5, 5, v158
	v_bfe_i32 v160, v2, 0, 16
	v_lshlrev_b32_e32 v2, 1, v3
	v_lshrrev_b32_e32 v4, 2, v3
	v_and_b32_e32 v6, 3, v159
	s_ashr_i32 s5, s23, 8
	v_and_b32_e32 v5, 32, v5
	v_and_b32_e32 v2, 24, v2
	v_and_b32_e32 v4, 4, v4
	v_and_or_b32 v6, v3, s3, v6
	v_bfe_u32 v162, v218, 4, 2
	s_lshl_b32 s26, s5, 6
	s_lshl_b32 s3, s6, 8
	v_or3_b32 v2, v6, v4, v2
	v_add_lshl_u32 v4, v5, v160, 1
	v_and_b32_e32 v173, 15, v218
	v_lshlrev_b32_e32 v161, 4, v162
	s_add_i32 s3, s3, s26
	s_ashr_i32 s4, s23, 6
	v_lshl_add_u32 v148, v2, 11, v4
	v_or3_b32 v2, s3, v173, v161
	s_ashr_i32 s7, s6, 31
	s_ashr_i32 s3, s2, 31
	s_lshl_b32 s51, s4, 10
	s_lshl_b64 s[10:11], s[6:7], 19
	s_lshl_b64 s[8:9], s[2:3], 19
	s_add_u32 s8, s49, s8
	v_lshl_add_u32 v146, v3, 11, v4
	v_ashrrev_i32_e32 v3, 31, v2
	s_addc_u32 s9, s50, s9
	s_add_i32 s52, s51, 0
	v_lshl_add_u64 v[2:3], v[2:3], 4, s[28:29]
	s_add_i32 m0, s52, 0x10000
	global_load_dwordx4 v[130:133], v[2:3], off
	global_load_dwordx4 v[134:137], v[2:3], off offset:2048
	s_waitcnt vmcnt(14)
	s_waitcnt vmcnt(10)
	global_load_lds_dwordx4 v144, s[8:9]
	s_add_i32 m0, s52, 0x12000
	s_add_u32 s34, s8, 0x40000
	global_load_lds_dwordx4 v148, s[8:9]
	s_addc_u32 s35, s9, 0
	s_add_i32 m0, s52, 0x14000
	v_mov_b32_e32 v145, v1
	global_load_lds_dwordx4 v144, s[34:35]
	s_add_i32 m0, s52, 0x16000
	s_add_u32 s10, s14, s10
	s_addc_u32 s11, s15, s11
	s_add_i32 s53, s52, 0x2000
	global_load_lds_dwordx4 v148, s[34:35]
	s_mov_b32 m0, s52
	s_add_u32 s34, s10, 0x40000
	global_load_lds_dwordx4 v142, s[10:11]
	s_mov_b32 m0, s53
	s_addc_u32 s35, s11, 0
	s_add_i32 s54, s52, 0x4000
	global_load_lds_dwordx4 v146, s[10:11]
	s_mov_b32 m0, s54
	s_add_i32 s55, s52, 0x6000
	global_load_lds_dwordx4 v142, s[34:35]
	s_mov_b32 m0, s55
	s_cmp_eq_u32 s5, 1
	global_load_lds_dwordx4 v146, s[34:35]
	s_cselect_b64 s[34:35], -1, 0
	v_mov_b32_e32 v149, v1
	v_mov_b32_e32 v143, v1
	v_mov_b32_e32 v147, v1
	v_writelane_b32 v255, s34, 53
	v_lshl_add_u64 v[150:151], s[8:9], 0, v[144:145]
	v_lshl_add_u64 v[140:141], s[8:9], 0, v[148:149]
	v_lshl_add_u64 v[138:139], s[10:11], 0, v[142:143]
	v_writelane_b32 v255, s35, 54
	s_cmp_lg_u32 s5, 1
	v_lshl_add_u64 v[152:153], s[10:11], 0, v[146:147]
	s_cbranch_scc1 .LBB0_91
	s_barrier

; #define PG8_STAGE(bufoff, gbase, voff) do { _Pragma("unroll") for (int _i = 0; _i < 2; ++_i) \
;         __builtin_amdgcn_global_load_lds((const unsigned*)((const char*)(gbase) + (voff)[_i]), (LAS unsigned*)(lds + (bufoff) + ldsw + _i * 8192), 16, 0, 0); } while (0)
; #define PG8_LDA(dst, b, h) do { _Pragma("unroll") for (int m = 0; m < 4; ++m) _Pragma("unroll") for (int k = 0; k < 2; ++k) dst[m][k] = *(const LAS bf16x8*)(lds + PG8_SA(b, h) + aoff + m * 2048 + k * 1024); } while (0)
; #define PG8_LDB(dst, b, h) do { _Pragma("unroll") for (int n = 0; n < 2; ++n) _Pragma("unroll") for (int k = 0; k < 2; ++k) dst[n][k] = *(const LAS bf16x8*)(lds + PG8_SB(b, h) + boff + n * 2048 + k * 1024); } while (0)
; #define PG8_MMA(ai, bj, At, Bt) do { __builtin_amdgcn_s_setprio(1); _Pragma("unroll") for (int m = 0; m < 4; ++m) _Pragma("unroll") for (int n = 0; n < 2; ++n) _Pragma("unroll") for (int k = 0; k < 2; ++k) \
;         acc[ai][bj][m][n] = __builtin_amdgcn_mfma_f32_16x16x32_bf16(Bt[n][k], At[m][k], acc[ai][bj][m][n], 0, 0, 0); __builtin_amdgcn_s_setprio(0); } while (0)
; #define PG8_WAIT_V(n) asm volatile("s_waitcnt vmcnt(" #n ")" ::: "memory")
; #define PG8_WAIT_L(n) asm volatile("s_waitcnt lgkmcnt(" #n ")" ::: "memory")
; #define PG8_BAR __builtin_amdgcn_s_barrier()
; #define PG8_SCHED __builtin_amdgcn_sched_barrier(0)
; template <class Epi>
; __device__ __forceinline__ void gemm_phase(LAS unsigned char* lds, const Gemm g, const Order& S, const Epi& E, const int tid) {
;     ...
;         for (int t = 0; t < nt; t += 2) {
;             const bool last = (t == nt - 2);
;             const char* a1 = cA + (size_t)(t + 1) * kstep;
;             const char* a2 = last ? nA : cA + (size_t)(t + 2) * kstep; const char* b2 = last ? nB : cB + (size_t)(t + 2) * kstep;
;             const char* a3 = a2 + kstep; const char* b3 = b2 + kstep;
;             PG8_LDB(B0, 0, 0); PG8_LDB(B1, 0, 1); PG8_SCHED; PG8_LDA(At, 0, 0); PG8_STAGE(PG8_SA(1, 1), a1 + hstep, voffA);
;             PG8_WAIT_V(8); PG8_WAIT_L(0); PG8_BAR; PG8_MMA(0, 0, At, B0); PG8_MMA(0, 1, At, B1); PG8_BAR; PG8_SCHED;
;             PG8_LDA(At, 0, 1); PG8_STAGE(PG8_SB(0, 0), b2, voffB); PG8_STAGE(PG8_SB(0, 1), b2 + hstep, voffB); PG8_STAGE(PG8_SA(0, 0), a2, voffA);
;             PG8_WAIT_V(8); PG8_WAIT_L(0); PG8_BAR; PG8_MMA(1, 0, At, B0); PG8_MMA(1, 1, At, B1); PG8_BAR; PG8_SCHED;
.LBB0_100:
	s_ashr_i32 s27, s26, 31
	s_lshl_b64 s[34:35], s[26:27], 19
	s_add_u32 s38, s14, s34
	s_addc_u32 s39, s15, s35
	s_and_b64 s[34:35], s[4:5], exec
	s_cselect_b32 s7, s39, s11
	s_cselect_b32 s27, s38, s10
	s_ashr_i32 s83, s82, 31
	s_lshl_b64 s[34:35], s[82:83], 19
	s_add_u32 s34, s49, s34
	s_addc_u32 s35, s50, s35
	s_and_b64 s[40:41], s[4:5], exec
	s_cselect_b32 s42, s35, s9
	s_cselect_b32 s43, s34, s8
	s_add_u32 s10, s10, 0x40080
	s_addc_u32 s11, s11, 0
	s_add_u32 s56, s8, 0x100
	s_addc_u32 s57, s9, 0
	s_mov_b32 s58, -2
	s_add_u32 s8, s10, 0xfffc0080
	s_addc_u32 s9, s11, -1
	s_add_i32 s59, 0, 0x10000
	s_cmp_eq_u32 s58, 12
	s_cselect_b32 s41, s7, s9
	s_cselect_b32 s40, s27, s8
	s_cselect_b32 s9, s42, s57
	s_cselect_b32 s8, s43, s56
	s_add_i32 s62, 0, 0x14000
	v_add_u32_e32 v156, s59, v179
	v_add_u32_e32 v172, s62, v179
	ds_read_b128 v[130:133], v156
	ds_read_b128 v[134:137], v156 offset:1024
	ds_read_b128 v[138:141], v156 offset:2048
	ds_read_b128 v[156:159], v156 offset:3072
	ds_read_b128 v[160:163], v172
	ds_read_b128 v[164:167], v172 offset:1024
	ds_read_b128 v[168:171], v172 offset:2048
	ds_read_b128 v[174:177], v172 offset:3072
	v_lshl_add_u64 v[198:199], s[10:11], 0, v[150:151]
	s_add_i32 m0, s52, 0xc000
	ds_read_b128 v[200:203], v193
	ds_read_b128 v[204:207], v193 offset:1024
	ds_read_b128 v[220:223], v193 offset:2048
	ds_read_b128 v[224:227], v193 offset:3072
	ds_read_b128 v[228:231], v193 offset:4096
	ds_read_b128 v[232:235], v193 offset:5120
	ds_read_b128 v[236:239], v193 offset:6144
	ds_read_b128 v[240:243], v193 offset:7168
	global_load_lds_dwordx4 v[198:199], off
	v_lshl_add_u64 v[198:199], s[10:11], 0, v[152:153]
	s_add_i32 m0, s52, 0xe000
	s_nop 0
	global_load_lds_dwordx4 v[198:199], off
	s_waitcnt vmcnt(8)
	s_waitcnt lgkmcnt(0)
	s_barrier
	s_setprio 1
	s_waitcnt lgkmcnt(0)
	v_mfma_f32_16x16x32_bf16 v[114:117], v[130:133], v[200:203], 0
	v_mfma_f32_16x16x32_bf16 v[118:121], v[138:141], v[200:203], 0
	v_mfma_f32_16x16x32_bf16 v[98:101], v[130:133], v[220:223], 0
	v_mfma_f32_16x16x32_bf16 v[102:105], v[138:141], v[220:223], 0
	v_mfma_f32_16x16x32_bf16 v[74:77], v[130:133], v[228:231], 0
	v_mfma_f32_16x16x32_bf16 v[78:81], v[138:141], v[228:231], 0
	v_mfma_f32_16x16x32_bf16 v[66:69], v[130:133], v[236:239], 0
	v_mfma_f32_16x16x32_bf16 v[70:73], v[138:141], v[236:239], 0
	v_mfma_f32_16x16x32_bf16 v[114:117], v[134:137], v[204:207], v[114:117]
	v_mfma_f32_16x16x32_bf16 v[118:121], v[156:159], v[204:207], v[118:121]
	v_mfma_f32_16x16x32_bf16 v[98:101], v[134:137], v[224:227], v[98:101]
	v_mfma_f32_16x16x32_bf16 v[102:105], v[156:159], v[224:227], v[102:105]
	v_mfma_f32_16x16x32_bf16 v[74:77], v[134:137], v[232:235], v[74:77]
	v_mfma_f32_16x16x32_bf16 v[78:81], v[156:159], v[232:235], v[78:81]
	v_mfma_f32_16x16x32_bf16 v[66:69], v[134:137], v[240:243], v[66:69]
	v_mfma_f32_16x16x32_bf16 v[70:73], v[156:159], v[240:243], v[70:73]
	s_setprio 0
	s_setprio 1
	v_mfma_f32_16x16x32_bf16 v[122:125], v[160:163], v[200:203], 0
	v_mfma_f32_16x16x32_bf16 v[126:129], v[168:171], v[200:203], 0
	v_mfma_f32_16x16x32_bf16 v[106:109], v[160:163], v[220:223], 0
	v_mfma_f32_16x16x32_bf16 v[110:113], v[168:171], v[220:223], 0
	v_mfma_f32_16x16x32_bf16 v[90:93], v[160:163], v[228:231], 0
	v_mfma_f32_16x16x32_bf16 v[94:97], v[168:171], v[228:231], 0
	v_mfma_f32_16x16x32_bf16 v[82:85], v[160:163], v[236:239], 0
	v_mfma_f32_16x16x32_bf16 v[86:89], v[168:171], v[236:239], 0
	v_mfma_f32_16x16x32_bf16 v[122:125], v[164:167], v[204:207], v[122:125]
	v_mfma_f32_16x16x32_bf16 v[126:129], v[174:177], v[204:207], v[126:129]
	v_mfma_f32_16x16x32_bf16 v[106:109], v[164:167], v[224:227], v[106:109]
	v_mfma_f32_16x16x32_bf16 v[110:113], v[174:177], v[224:227], v[110:113]
	v_mfma_f32_16x16x32_bf16 v[90:93], v[164:167], v[232:235], v[90:93]
	v_mfma_f32_16x16x32_bf16 v[94:97], v[174:177], v[232:235], v[94:97]
	v_mfma_f32_16x16x32_bf16 v[82:85], v[164:167], v[240:243], v[82:85]
	v_mfma_f32_16x16x32_bf16 v[86:89], v[174:177], v[240:243], v[86:89]
	s_setprio 0
	s_barrier
	s_add_i32 s59, s59, s51
	v_lshl_add_u64 v[198:199], s[8:9], 0, v[144:145]
	s_mov_b32 m0, s59
	ds_read_b128 v[200:203], v193 offset:16384
	ds_read_b128 v[204:207], v193 offset:17408
	ds_read_b128 v[220:223], v193 offset:18432
	ds_read_b128 v[224:227], v193 offset:19456
	ds_read_b128 v[228:231], v193 offset:20480
	ds_read_b128 v[232:235], v193 offset:21504
	ds_read_b128 v[236:239], v193 offset:22528
	ds_read_b128 v[240:243], v193 offset:23552
	global_load_lds_dwordx4 v[198:199], off
	s_add_i32 m0, s59, 0x2000
	s_add_u32 s60, s8, 0x40000
	v_lshl_add_u64 v[244:245], s[8:9], 0, v[148:149]
	s_addc_u32 s61, s9, 0
	s_add_i32 s59, s62, s51
	global_load_lds_dwordx4 v[244:245], off
	v_lshl_add_u64 v[246:247], s[60:61], 0, v[144:145]
	s_mov_b32 m0, s59
	v_lshl_add_u64 v[248:249], s[40:41], 0, v[146:147]
	global_load_lds_dwordx4 v[246:247], off
	v_lshl_add_u64 v[246:247], s[60:61], 0, v[148:149]
	s_add_i32 m0, s59, 0x2000
	s_nop 0
	global_load_lds_dwordx4 v[246:247], off
	v_lshl_add_u64 v[246:247], s[40:41], 0, v[142:143]
	s_mov_b32 m0, s52
	s_nop 0
	global_load_lds_dwordx4 v[246:247], off
	s_mov_b32 m0, s53
	s_nop 0
	global_load_lds_dwordx4 v[248:249], off
	s_waitcnt vmcnt(8)
	s_waitcnt lgkmcnt(0)
	s_barrier
; #define PG8_STAGE(bufoff, gbase, voff) do { _Pragma("unroll") for (int _i = 0; _i < 2; ++_i) \
;         __builtin_amdgcn_global_load_lds((const unsigned*)((const char*)(gbase) + (voff)[_i]), (LAS unsigned*)(lds + (bufoff) + ldsw + _i * 8192), 16, 0, 0); } while (0)
; #define PG8_LDA(dst, b, h) do { _Pragma("unroll") for (int m = 0; m < 4; ++m) _Pragma("unroll") for (int k = 0; k < 2; ++k) dst[m][k] = *(const LAS bf16x8*)(lds + PG8_SA(b, h) + aoff + m * 2048 + k * 1024); } while (0)
; #define PG8_LDB(dst, b, h) do { _Pragma("unroll") for (int n = 0; n < 2; ++n) _Pragma("unroll") for (int k = 0; k < 2; ++k) dst[n][k] = *(const LAS bf16x8*)(lds + PG8_SB(b, h) + boff + n * 2048 + k * 1024); } while (0)
; #define PG8_MMA(ai, bj, At, Bt) do { __builtin_amdgcn_s_setprio(1); _Pragma("unroll") for (int m = 0; m < 4; ++m) _Pragma("unroll") for (int n = 0; n < 2; ++n) _Pragma("unroll") for (int k = 0; k < 2; ++k) \
;         acc[ai][bj][m][n] = __builtin_amdgcn_mfma_f32_16x16x32_bf16(Bt[n][k], At[m][k], acc[ai][bj][m][n], 0, 0, 0); __builtin_amdgcn_s_setprio(0); } while (0)
; #define PG8_WAIT_V(n) asm volatile("s_waitcnt vmcnt(" #n ")" ::: "memory")
; #define PG8_WAIT_L(n) asm volatile("s_waitcnt lgkmcnt(" #n ")" ::: "memory")
; #define PG8_BAR __builtin_amdgcn_s_barrier()
; #define PG8_SCHED __builtin_amdgcn_sched_barrier(0)
; template <class Epi>
; __device__ __forceinline__ void gemm_phase(LAS unsigned char* lds, const Gemm g, const Order& S, const Epi& E, const int tid) {
;     ...
;             PG8_WAIT_V(8); PG8_WAIT_L(0); PG8_BAR; PG8_MMA(1, 0, At, B0); PG8_MMA(1, 1, At, B1); PG8_BAR; PG8_SCHED;
;             PG8_LDB(B0, 1, 0); PG8_LDB(B1, 1, 1); PG8_SCHED; PG8_LDA(At, 1, 0); PG8_STAGE(PG8_SA(0, 1), a2 + hstep, voffA);
;             PG8_WAIT_V(8); PG8_WAIT_L(0); PG8_BAR; PG8_MMA(0, 0, At, B0); PG8_MMA(0, 1, At, B1); PG8_BAR; PG8_SCHED;
;             PG8_LDA(At, 1, 1); PG8_STAGE(PG8_SB(1, 0), b3, voffB); PG8_STAGE(PG8_SB(1, 1), b3 + hstep, voffB); PG8_STAGE(PG8_SA(1, 0), a3, voffA);
;             PG8_WAIT_V(8); PG8_WAIT_L(0); PG8_BAR; PG8_MMA(1, 0, At, B0); PG8_MMA(1, 1, At, B1); PG8_BAR; PG8_SCHED;
	s_setprio 1
	s_waitcnt lgkmcnt(0)
	v_mfma_f32_16x16x32_bf16 v[42:45], v[130:133], v[200:203], 0
	v_mfma_f32_16x16x32_bf16 v[46:49], v[138:141], v[200:203], 0
	v_mfma_f32_16x16x32_bf16 v[34:37], v[130:133], v[220:223], 0
	v_mfma_f32_16x16x32_bf16 v[38:41], v[138:141], v[220:223], 0
	v_mfma_f32_16x16x32_bf16 v[10:13], v[130:133], v[228:231], 0
	v_mfma_f32_16x16x32_bf16 v[14:17], v[138:141], v[228:231], 0
	v_mfma_f32_16x16x32_bf16 v[2:5], v[130:133], v[236:239], 0
	v_mfma_f32_16x16x32_bf16 v[6:9], v[138:141], v[236:239], 0
	v_mfma_f32_16x16x32_bf16 v[42:45], v[134:137], v[204:207], v[42:45]
	v_mfma_f32_16x16x32_bf16 v[46:49], v[156:159], v[204:207], v[46:49]
	v_mfma_f32_16x16x32_bf16 v[34:37], v[134:137], v[224:227], v[34:37]
	v_mfma_f32_16x16x32_bf16 v[38:41], v[156:159], v[224:227], v[38:41]
	v_mfma_f32_16x16x32_bf16 v[10:13], v[134:137], v[232:235], v[10:13]
	v_mfma_f32_16x16x32_bf16 v[14:17], v[156:159], v[232:235], v[14:17]
	v_mfma_f32_16x16x32_bf16 v[2:5], v[134:137], v[240:243], v[2:5]
	v_mfma_f32_16x16x32_bf16 v[6:9], v[156:159], v[240:243], v[6:9]
	s_setprio 0
	s_setprio 1
	v_mfma_f32_16x16x32_bf16 v[58:61], v[160:163], v[200:203], 0
	v_mfma_f32_16x16x32_bf16 v[62:65], v[168:171], v[200:203], 0
	v_mfma_f32_16x16x32_bf16 v[50:53], v[160:163], v[220:223], 0
	v_mfma_f32_16x16x32_bf16 v[54:57], v[168:171], v[220:223], 0
	v_mfma_f32_16x16x32_bf16 v[26:29], v[160:163], v[228:231], 0
	v_mfma_f32_16x16x32_bf16 v[30:33], v[168:171], v[228:231], 0
	v_mfma_f32_16x16x32_bf16 v[18:21], v[160:163], v[236:239], 0
	v_mfma_f32_16x16x32_bf16 v[22:25], v[168:171], v[236:239], 0
	v_mfma_f32_16x16x32_bf16 v[58:61], v[164:167], v[204:207], v[58:61]
	v_mfma_f32_16x16x32_bf16 v[62:65], v[174:177], v[204:207], v[62:65]
	v_mfma_f32_16x16x32_bf16 v[50:53], v[164:167], v[224:227], v[50:53]
	v_mfma_f32_16x16x32_bf16 v[54:57], v[174:177], v[224:227], v[54:57]
	v_mfma_f32_16x16x32_bf16 v[26:29], v[164:167], v[232:235], v[26:29]
	v_mfma_f32_16x16x32_bf16 v[30:33], v[174:177], v[232:235], v[30:33]
	v_mfma_f32_16x16x32_bf16 v[18:21], v[164:167], v[240:243], v[18:21]
	v_mfma_f32_16x16x32_bf16 v[22:25], v[174:177], v[240:243], v[22:25]
	s_setprio 0
	s_barrier
	s_add_i32 s59, 0, 0x18000
	s_add_i32 s60, 0, 0x1c000
	v_add_u32_e32 v156, s59, v179
	v_add_u32_e32 v172, s60, v179
	ds_read_b128 v[130:133], v156
	ds_read_b128 v[134:137], v156 offset:1024
	ds_read_b128 v[138:141], v156 offset:2048
	ds_read_b128 v[156:159], v156 offset:3072
	ds_read_b128 v[160:163], v172
	ds_read_b128 v[164:167], v172 offset:1024
	ds_read_b128 v[168:171], v172 offset:2048
	ds_read_b128 v[174:177], v172 offset:3072
	s_add_u32 s40, s40, 0x40000
	s_addc_u32 s41, s41, 0
	s_mov_b32 m0, s54
	v_lshl_add_u64 v[250:251], s[40:41], 0, v[142:143]
	ds_read_b128 v[200:203], v193 offset:32768
	ds_read_b128 v[204:207], v193 offset:33792
	ds_read_b128 v[220:223], v193 offset:34816
	ds_read_b128 v[224:227], v193 offset:35840
	ds_read_b128 v[228:231], v193 offset:36864
	ds_read_b128 v[232:235], v193 offset:37888
	ds_read_b128 v[236:239], v193 offset:38912
	ds_read_b128 v[240:243], v193 offset:39936
	global_load_lds_dwordx4 v[250:251], off
	v_lshl_add_u64 v[250:251], s[40:41], 0, v[146:147]
	s_mov_b32 m0, s55
	s_nop 0
	global_load_lds_dwordx4 v[250:251], off
	s_waitcnt vmcnt(8)
	s_waitcnt lgkmcnt(0)
	s_barrier
	s_setprio 1
	s_waitcnt lgkmcnt(0)
	v_mfma_f32_16x16x32_bf16 v[114:117], v[130:133], v[200:203], v[114:117]
	v_mfma_f32_16x16x32_bf16 v[118:121], v[138:141], v[200:203], v[118:121]
	v_mfma_f32_16x16x32_bf16 v[98:101], v[130:133], v[220:223], v[98:101]
	v_mfma_f32_16x16x32_bf16 v[102:105], v[138:141], v[220:223], v[102:105]
	v_mfma_f32_16x16x32_bf16 v[74:77], v[130:133], v[228:231], v[74:77]
	v_mfma_f32_16x16x32_bf16 v[78:81], v[138:141], v[228:231], v[78:81]
	v_mfma_f32_16x16x32_bf16 v[66:69], v[130:133], v[236:239], v[66:69]
	v_mfma_f32_16x16x32_bf16 v[70:73], v[138:141], v[236:239], v[70:73]
	v_mfma_f32_16x16x32_bf16 v[114:117], v[134:137], v[204:207], v[114:117]
	v_mfma_f32_16x16x32_bf16 v[118:121], v[156:159], v[204:207], v[118:121]
	v_mfma_f32_16x16x32_bf16 v[98:101], v[134:137], v[224:227], v[98:101]
	v_mfma_f32_16x16x32_bf16 v[102:105], v[156:159], v[224:227], v[102:105]
	v_mfma_f32_16x16x32_bf16 v[74:77], v[134:137], v[232:235], v[74:77]
	v_mfma_f32_16x16x32_bf16 v[78:81], v[156:159], v[232:235], v[78:81]
	v_mfma_f32_16x16x32_bf16 v[66:69], v[134:137], v[240:243], v[66:69]
	v_mfma_f32_16x16x32_bf16 v[70:73], v[156:159], v[240:243], v[70:73]
	s_setprio 0
	s_setprio 1
	v_mfma_f32_16x16x32_bf16 v[122:125], v[160:163], v[200:203], v[122:125]
	v_mfma_f32_16x16x32_bf16 v[126:129], v[168:171], v[200:203], v[126:129]
	v_mfma_f32_16x16x32_bf16 v[106:109], v[160:163], v[220:223], v[106:109]
	v_mfma_f32_16x16x32_bf16 v[110:113], v[168:171], v[220:223], v[110:113]
	v_mfma_f32_16x16x32_bf16 v[90:93], v[160:163], v[228:231], v[90:93]
	v_mfma_f32_16x16x32_bf16 v[94:97], v[168:171], v[228:231], v[94:97]
	v_mfma_f32_16x16x32_bf16 v[82:85], v[160:163], v[236:239], v[82:85]
	v_mfma_f32_16x16x32_bf16 v[86:89], v[168:171], v[236:239], v[86:89]
	v_mfma_f32_16x16x32_bf16 v[122:125], v[164:167], v[204:207], v[122:125]
	v_mfma_f32_16x16x32_bf16 v[126:129], v[174:177], v[204:207], v[126:129]
	v_mfma_f32_16x16x32_bf16 v[106:109], v[164:167], v[224:227], v[106:109]
	v_mfma_f32_16x16x32_bf16 v[110:113], v[174:177], v[224:227], v[110:113]
	v_mfma_f32_16x16x32_bf16 v[90:93], v[164:167], v[232:235], v[90:93]
	v_mfma_f32_16x16x32_bf16 v[94:97], v[174:177], v[232:235], v[94:97]
	v_mfma_f32_16x16x32_bf16 v[82:85], v[164:167], v[240:243], v[82:85]
	v_mfma_f32_16x16x32_bf16 v[86:89], v[174:177], v[240:243], v[86:89]
	s_setprio 0
	s_barrier
; #define PG8_STAGE(bufoff, gbase, voff) do { _Pragma("unroll") for (int _i = 0; _i < 2; ++_i) \
;         __builtin_amdgcn_global_load_lds((const unsigned*)((const char*)(gbase) + (voff)[_i]), (LAS unsigned*)(lds + (bufoff) + ldsw + _i * 8192), 16, 0, 0); } while (0)
; #define PG8_LDA(dst, b, h) do { _Pragma("unroll") for (int m = 0; m < 4; ++m) _Pragma("unroll") for (int k = 0; k < 2; ++k) dst[m][k] = *(const LAS bf16x8*)(lds + PG8_SA(b, h) + aoff + m * 2048 + k * 1024); } while (0)
; #define PG8_MMA(ai, bj, At, Bt) do { __builtin_amdgcn_s_setprio(1); _Pragma("unroll") for (int m = 0; m < 4; ++m) _Pragma("unroll") for (int n = 0; n < 2; ++n) _Pragma("unroll") for (int k = 0; k < 2; ++k) \
;         acc[ai][bj][m][n] = __builtin_amdgcn_mfma_f32_16x16x32_bf16(Bt[n][k], At[m][k], acc[ai][bj][m][n], 0, 0, 0); __builtin_amdgcn_s_setprio(0); } while (0)
; #define PG8_WAIT_V(n) asm volatile("s_waitcnt vmcnt(" #n ")" ::: "memory")
; #define PG8_WAIT_L(n) asm volatile("s_waitcnt lgkmcnt(" #n ")" ::: "memory")
; #define PG8_BAR __builtin_amdgcn_s_barrier()
; #define PG8_SCHED __builtin_amdgcn_sched_barrier(0)
; template <class Epi>
; __device__ __forceinline__ void gemm_phase(LAS unsigned char* lds, const Gemm g, const Order& S, const Epi& E, const int tid) {
;     ...
;             PG8_LDA(At, 1, 1); PG8_STAGE(PG8_SB(1, 0), b3, voffB); PG8_STAGE(PG8_SB(1, 1), b3 + hstep, voffB); PG8_STAGE(PG8_SA(1, 0), a3, voffA);
;             PG8_WAIT_V(8); PG8_WAIT_L(0); PG8_BAR; PG8_MMA(1, 0, At, B0); PG8_MMA(1, 1, At, B1); PG8_BAR; PG8_SCHED;
;         }
	s_add_i32 s40, s59, s51
	v_lshl_add_u64 v[198:199], v[198:199], 0, s[86:87]
	s_mov_b32 m0, s40
	ds_read_b128 v[200:203], v193 offset:49152
	ds_read_b128 v[204:207], v193 offset:50176
	ds_read_b128 v[220:223], v193 offset:51200
	ds_read_b128 v[224:227], v193 offset:52224
	ds_read_b128 v[228:231], v193 offset:53248
	ds_read_b128 v[232:235], v193 offset:54272
	ds_read_b128 v[236:239], v193 offset:55296
	ds_read_b128 v[240:243], v193 offset:56320
	global_load_lds_dwordx4 v[198:199], off
	s_add_i32 m0, s40, 0x2000
	s_add_u32 s8, s8, 0x40080
	v_lshl_add_u64 v[198:199], v[244:245], 0, s[86:87]
	s_addc_u32 s9, s9, 0
	s_add_i32 s40, s60, s51
	global_load_lds_dwordx4 v[198:199], off
	v_lshl_add_u64 v[198:199], s[8:9], 0, v[144:145]
	s_mov_b32 m0, s40
	s_nop 0
	global_load_lds_dwordx4 v[198:199], off
	v_lshl_add_u64 v[198:199], s[8:9], 0, v[148:149]
	s_add_i32 m0, s40, 0x2000
	s_nop 0
	global_load_lds_dwordx4 v[198:199], off
	v_lshl_add_u64 v[198:199], v[246:247], 0, s[86:87]
	s_mov_b32 m0, s74
	s_nop 0
	global_load_lds_dwordx4 v[198:199], off
	v_lshl_add_u64 v[198:199], v[248:249], 0, s[86:87]
	s_mov_b32 m0, s75
	s_nop 0
	global_load_lds_dwordx4 v[198:199], off
	s_waitcnt vmcnt(8)
	s_waitcnt lgkmcnt(0)
	s_barrier
	s_setprio 1
	s_waitcnt lgkmcnt(0)
	v_mfma_f32_16x16x32_bf16 v[42:45], v[130:133], v[200:203], v[42:45]
	v_mfma_f32_16x16x32_bf16 v[46:49], v[138:141], v[200:203], v[46:49]
	v_mfma_f32_16x16x32_bf16 v[34:37], v[130:133], v[220:223], v[34:37]
	v_mfma_f32_16x16x32_bf16 v[38:41], v[138:141], v[220:223], v[38:41]
	v_mfma_f32_16x16x32_bf16 v[10:13], v[130:133], v[228:231], v[10:13]
	v_mfma_f32_16x16x32_bf16 v[14:17], v[138:141], v[228:231], v[14:17]
	v_mfma_f32_16x16x32_bf16 v[2:5], v[130:133], v[236:239], v[2:5]
	v_mfma_f32_16x16x32_bf16 v[6:9], v[138:141], v[236:239], v[6:9]
	v_mfma_f32_16x16x32_bf16 v[42:45], v[134:137], v[204:207], v[42:45]
	v_mfma_f32_16x16x32_bf16 v[46:49], v[156:159], v[204:207], v[46:49]
	v_mfma_f32_16x16x32_bf16 v[34:37], v[134:137], v[224:227], v[34:37]
	v_mfma_f32_16x16x32_bf16 v[38:41], v[156:159], v[224:227], v[38:41]
	v_mfma_f32_16x16x32_bf16 v[10:13], v[134:137], v[232:235], v[10:13]
	v_mfma_f32_16x16x32_bf16 v[14:17], v[156:159], v[232:235], v[14:17]
	v_mfma_f32_16x16x32_bf16 v[2:5], v[134:137], v[240:243], v[2:5]
	v_mfma_f32_16x16x32_bf16 v[6:9], v[156:159], v[240:243], v[6:9]
	s_setprio 0
	s_setprio 1
	v_mfma_f32_16x16x32_bf16 v[58:61], v[160:163], v[200:203], v[58:61]
	v_mfma_f32_16x16x32_bf16 v[62:65], v[168:171], v[200:203], v[62:65]
	v_mfma_f32_16x16x32_bf16 v[50:53], v[160:163], v[220:223], v[50:53]
	v_mfma_f32_16x16x32_bf16 v[54:57], v[168:171], v[220:223], v[54:57]
	v_mfma_f32_16x16x32_bf16 v[26:29], v[160:163], v[228:231], v[26:29]
	v_mfma_f32_16x16x32_bf16 v[30:33], v[168:171], v[228:231], v[30:33]
	v_mfma_f32_16x16x32_bf16 v[18:21], v[160:163], v[236:239], v[18:21]
	v_mfma_f32_16x16x32_bf16 v[22:25], v[168:171], v[236:239], v[22:25]
	v_mfma_f32_16x16x32_bf16 v[58:61], v[164:167], v[204:207], v[58:61]
	v_mfma_f32_16x16x32_bf16 v[62:65], v[174:177], v[204:207], v[62:65]
	v_mfma_f32_16x16x32_bf16 v[50:53], v[164:167], v[224:227], v[50:53]
	v_mfma_f32_16x16x32_bf16 v[54:57], v[174:177], v[224:227], v[54:57]
	v_mfma_f32_16x16x32_bf16 v[26:29], v[164:167], v[232:235], v[26:29]
	v_mfma_f32_16x16x32_bf16 v[30:33], v[174:177], v[232:235], v[30:33]
	v_mfma_f32_16x16x32_bf16 v[18:21], v[164:167], v[240:243], v[18:21]
	v_mfma_f32_16x16x32_bf16 v[22:25], v[174:177], v[240:243], v[22:25]
	s_setprio 0
	s_barrier
	s_add_i32 s58, s58, 2
	s_add_u32 s10, s10, 0x100
	s_addc_u32 s11, s11, 0
	s_add_u32 s56, s56, 0x100
	s_addc_u32 s57, s57, 0
	s_cmp_gt_u32 s58, 13

; #define PG8_BAR __builtin_amdgcn_s_barrier()
; __device__ __forceinline__ void rstd_finish(const f32x4& raw0, const f32x4& raw1, float& rn0, float& rn1) {
;     rn0 = rsqrtf(((raw0.x + raw0.y) + (raw0.z + raw0.w)) * (1.f / DM) + EPS); rn1 = rsqrtf(((raw1.x + raw1.y) + (raw1.z + raw1.w)) * (1.f / DM) + EPS);
;     asm volatile("" :: "v"(rn0), "v"(rn1) : "memory");
; template <class Epi>
; __device__ __forceinline__ void gemm_phase(LAS unsigned char* lds, const Gemm g, const Order& S, const Epi& E, const int tid) {
;     ...
;         if constexpr (Epi::NEEDS_RSTD && !Epi::EARLY_RSTD) rstd_finish(raw0, raw1, rn0, rn1);
;         rp0 = rn0; rp1 = rn1;
;         if (!has_next) break;
; #pragma unroll
;         for (int a = 0; a < 2; ++a)
; #pragma unroll
;             for (int b = 0; b < 2; ++b)
; #pragma unroll
;                 for (int m = 0; m < 4; ++m)
; #pragma unroll
;                     for (int n = 0; n < 2; ++n) { double zl, zh; asm volatile("v_mov_b64 %0, 0\n\tv_mov_b64 %1, 0" : "=v"(zl), "=v"(zh)); d64x2 zz = {zl, zh}; acc[a][b][m][n] = __builtin_bit_cast(f32x4, zz); }
;         cur = nxt; cA = nA; cB = nB; ++ui;
;         if (wr == 1) PG8_BAR;
.LBB0_167:
	s_nop 1
	v_lshl_add_u64 v[2:3], v[156:157], 0, s[2:3]
	global_store_dwordx4 v[2:3], v[138:141], off offset:64
	s_waitcnt vmcnt(0)
	v_mov_b32_e32 v2, v135
	v_mov_b32_e32 v3, v136
	v_mov_b32_e32 v135, v137
	v_mov_b32_e32 v4, v131
	v_mov_b32_e32 v5, v132
	v_mov_b32_e32 v131, v133
	v_pk_add_f32 v[2:3], v[2:3], v[134:135]
	v_pk_add_f32 v[4:5], v[4:5], v[130:131]
	v_mov_b32_e32 v7, v2
	v_mov_b32_e32 v6, v4
	v_mov_b32_e32 v2, v5
	v_pk_add_f32 v[2:3], v[6:7], v[2:3]
	s_mov_b64 s[2:3], -1
	v_pk_fma_f32 v[2:3], v[2:3], s[84:85], v[182:183] op_sel_hi:[1,0,0]
	s_nop 0
	v_mul_f32_e32 v4, 0x4b800000, v3
	v_cmp_gt_f32_e64 s[6:7], s89, v3
	v_cmp_gt_f32_e32 vcc, s89, v2
	s_nop 0
	v_cndmask_b32_e64 v3, v3, v4, s[6:7]
	v_mul_f32_e32 v4, 0x4b800000, v2
	v_cndmask_b32_e32 v2, v2, v4, vcc
	v_rsq_f32_e32 v3, v3
	v_rsq_f32_e32 v2, v2
	s_nop 0
	v_pk_mul_f32 v[4:5], v[2:3], s[78:79] op_sel_hi:[1,0]
	s_nop 0
	v_cndmask_b32_e64 v155, v3, v5, s[6:7]
	v_cndmask_b32_e32 v154, v2, v4, vcc
	s_andn2_b64 vcc, exec, s[4:5]
	s_cbranch_vccnz .LBB0_93
	v_readlane_b32 s2, v255, 53
	v_readlane_b32 s3, v255, 54
	s_andn2_b64 vcc, exec, s[2:3]
	s_cbranch_vccnz .LBB0_92
	s_barrier
	s_branch .LBB0_92

; #define PG8_STAGE(bufoff, gbase, voff) do { _Pragma("unroll") for (int _i = 0; _i < 2; ++_i) \
;         __builtin_amdgcn_global_load_lds((const unsigned*)((const char*)(gbase) + (voff)[_i]), (LAS unsigned*)(lds + (bufoff) + ldsw + _i * 8192), 16, 0, 0); } while (0)
; template <class Epi>
; __device__ __forceinline__ void gemm_phase(LAS unsigned char* lds, const Gemm g, const Order& S, const Epi& E, const int tid) {
;     const int wid = __builtin_amdgcn_readfirstlane(tid >> 6), lane = tid & 63, wr = wid >> 2, wc = wid & 3, fr = lane & 15, fq = lane >> 4;
;     const int K = g.K, nt = K / BK;
;     unsigned voffA[2], voffB[2];
; #pragma unroll
;     for (int i = 0; i < 2; ++i) { int R, C; stage_rc(tid * 16 + i * 8192, R, C); const int Rb = (R & ~31) + perm32(R & 31);
;         voffA[i] = (unsigned)(R * K + C) * 2u; voffB[i] = (unsigned)(Rb * K + C) * 2u; }
;     const size_t kstep = (size_t)(BK * 2);
;     const size_t hstep = (size_t)HALF * K * 2;
;     const size_t tstep = 2 * hstep;
;     const unsigned ldsw = (unsigned)wid * 1024u;
;     const int aoff = lds_byte(wr * 64 + fr, fq * 8), boff = lds_byte(wc * 32 + fr, fq * 8);
;     ...
;     Unit cur, nxt; int ui = 0;
;     if (!S.next(0, cur)) return;
;     float rp0 = 0.f, rp1 = 0.f;
;     if constexpr (Epi::NEEDS_RSTD) { const int rr = cur.pm * BM + wr * 64 + fr + 16 * fq; rp0 = row_rstd(E.ssq, rr); rp1 = row_rstd(E.ssq, rr + HALF); }
;     f32x4 acc[2][2][4][2];
; #pragma unroll
;     for (int a = 0; a < 2; ++a)
; #pragma unroll
;         for (int b = 0; b < 2; ++b)
; #pragma unroll
;             for (int m = 0; m < 4; ++m)
; #pragma unroll
;                 for (int n = 0; n < 2; ++n) { double zl, zh; asm volatile("v_mov_b64 %0, 0\n\tv_mov_b64 %1, 0" : "=v"(zl), "=v"(zh)); d64x2 zz = {zl, zh}; acc[a][b][m][n] = __builtin_bit_cast(f32x4, zz); }
;     bf16x8 At[4][2], B0[2][2], B1[2][2];
;     const char* cA = (const char*)g.A + (size_t)cur.pm * tstep; const char* cB = (const char*)g.Bt + (size_t)cur.pn * tstep;
;     PG8_STAGE(PG8_SB(0, 0), cB, voffB); PG8_STAGE(PG8_SB(0, 1), cB + hstep, voffB); PG8_STAGE(PG8_SA(0, 0), cA, voffA); PG8_STAGE(PG8_SA(0, 1), cA + hstep, voffA);
;     if (wr == 1) PG8_BAR;
;     PG8_WAIT_V(2); PG8_BAR;
;     PG8_STAGE(PG8_SB(1, 0), cB + kstep, voffB); PG8_STAGE(PG8_SA(1, 0), cA + kstep, voffA); PG8_STAGE(PG8_SB(1, 1), cB + hstep + kstep, voffB);
;     PG8_WAIT_V(6); PG8_BAR;
.LBB0_187:
	s_andn2_b64 vcc, exec, s[8:9]
	s_cbranch_vccnz .LBB0_309
	v_bfe_i32 v2, v218, 27, 1
	v_lshlrev_b32_e32 v166, 4, v218
	v_lshrrev_b32_e32 v2, 22, v2
	v_add_u32_e32 v2, v166, v2
	v_and_b32_e32 v2, 0xfffffc00, v2
	v_sub_u32_e32 v2, v166, v2
	v_ashrrev_i32_e32 v0, 31, v218
	v_lshrrev_b32_e32 v3, 4, v2
	v_lshrrev_b32_e32 v0, 26, v0
	v_bitop3_b32 v2, v3, v2, 32 bitop3:0x6c
	v_add_u32_e32 v0, v218, v0
	v_ashrrev_i32_e32 v4, 31, v2
	v_ashrrev_i32_e32 v0, 6, v0
	v_lshrrev_b32_e32 v4, 26, v4
	v_lshlrev_b32_e32 v3, 3, v0
	v_add_u32_e32 v4, v2, v4
	v_and_b32_e32 v3, -16, v3
	v_ashrrev_i32_e32 v5, 6, v4
	v_lshlrev_b32_e32 v0, 5, v0
	s_add_u32 s33, s18, s6
	v_add_u32_e32 v3, v5, v3
	v_and_b32_e32 v142, 32, v0
	v_and_b32_e32 v0, 0xc0, v4
	s_addc_u32 s42, s19, s7
	v_sub_u32_e32 v0, v2, v0
	v_lshlrev_b32_e32 v2, 1, v3
	v_lshrrev_b32_e32 v4, 2, v3
	v_and_b32_e32 v5, 3, v5
	s_mov_b32 s7, 0x7fffffe0
	v_ashrrev_i16_sdwa v0, v183, sext(v0) dst_sel:DWORD dst_unused:UNUSED_PAD src0_sel:DWORD src1_sel:BYTE_0
	v_and_b32_e32 v2, 24, v2
	v_and_b32_e32 v4, 4, v4
	v_and_or_b32 v5, v3, s7, v5
	v_bfe_i32 v143, v0, 0, 16
	v_or3_b32 v2, v5, v4, v2
	v_add_u32_e32 v0, v142, v143
	v_mul_lo_u32 v144, s3, v3
	v_mul_lo_u32 v2, s3, v2
	v_add_lshl_u32 v150, v144, v0, 1
	v_add_lshl_u32 v0, v2, v0, 1
	v_add_u32_e32 v2, 0x2000, v166
	v_ashrrev_i32_e32 v3, 31, v2
	v_lshrrev_b32_e32 v3, 22, v3
	v_add_u32_e32 v3, v2, v3
	v_ashrrev_i32_e32 v3, 10, v3
	v_mul_i32_i24_e32 v4, 0x400, v3
	v_sub_u32_e32 v2, v2, v4
	v_lshrrev_b32_e32 v4, 4, v2
	v_bitop3_b32 v2, v4, v2, 32 bitop3:0x6c
	v_ashrrev_i32_e32 v5, 31, v2
	v_lshrrev_b32_e32 v5, 26, v5
	v_lshlrev_b32_e32 v4, 3, v3
	v_add_u32_e32 v5, v2, v5
	v_and_b32_e32 v4, -16, v4
	v_ashrrev_i32_e32 v6, 6, v5
	s_ashr_i32 s6, s26, 6
	v_add_u32_e32 v4, v6, v4
	v_and_b32_e32 v6, 3, v6
	v_lshlrev_b32_e32 v3, 5, v3
	v_and_or_b32 v6, v4, s7, v6
	s_ashr_i32 s7, s26, 8
	s_lshl_b32 s76, s3, 8
	s_lshl_b32 s43, s3, 9
	s_lshl_b32 s48, s6, 10
	v_and_b32_e32 v145, 32, v3
	v_and_b32_e32 v3, 0xc0, v5
	s_and_b64 s[4:5], s[4:5], exec
	v_sub_u32_e32 v2, v2, v3
	v_lshlrev_b32_e32 v3, 1, v4
	v_lshrrev_b32_e32 v5, 2, v4
	s_mul_i32 s5, s43, s20
	s_mov_b32 s62, s50
	v_ashrrev_i16_sdwa v2, v183, sext(v2) dst_sel:DWORD dst_unused:UNUSED_PAD src0_sel:DWORD src1_sel:BYTE_0
	v_and_b32_e32 v3, 24, v3
	v_and_b32_e32 v5, 4, v5
	s_cselect_b32 s49, s13, s25
	s_cselect_b32 s50, s12, s24
	s_mul_hi_i32 s4, s43, s20
	s_add_u32 s12, s33, s5
	v_bfe_i32 v146, v2, 0, 16
	v_or3_b32 v3, v6, v5, v3
	s_addc_u32 s13, s42, s4
	s_add_i32 s51, s48, 0
	v_add_u32_e32 v2, v145, v146
	v_mul_lo_u32 v147, s3, v4
	v_mul_lo_u32 v3, s3, v3
	s_add_i32 m0, s51, 0x10000
	v_add_lshl_u32 v152, v147, v2, 1
	v_add_lshl_u32 v154, v3, v2, 1
	s_waitcnt vmcnt(12)
	s_waitcnt vmcnt(9)
	s_waitcnt vmcnt(8)
	global_load_lds_dwordx4 v0, s[12:13]
	s_add_i32 m0, s51, 0x12000
	s_add_u32 s4, s12, s76
	global_load_lds_dwordx4 v154, s[12:13]
	s_addc_u32 s5, s13, 0
	s_add_i32 m0, s51, 0x14000
	s_mul_i32 s9, s43, s21
	global_load_lds_dwordx4 v0, s[4:5]
	s_add_i32 m0, s51, 0x16000
	s_mul_hi_i32 s8, s43, s21
	s_add_u32 s40, s50, s9
	v_mov_b32_e32 v155, v1
	s_addc_u32 s41, s49, s8
	s_add_i32 s52, s51, 0x2000
	v_lshl_add_u64 v[134:135], s[4:5], 0, v[0:1]
	v_lshl_add_u64 v[136:137], s[4:5], 0, v[154:155]
	global_load_lds_dwordx4 v154, s[4:5]
	s_mov_b32 m0, s51
	s_add_u32 s4, s40, s76
	global_load_lds_dwordx4 v150, s[40:41]
	s_mov_b32 m0, s52
	s_addc_u32 s5, s41, 0
	s_add_i32 s53, s51, 0x4000
	global_load_lds_dwordx4 v152, s[40:41]
	s_mov_b32 m0, s53
	s_add_i32 s54, s51, 0x6000
	global_load_lds_dwordx4 v150, s[4:5]
	s_mov_b32 m0, s54
	v_mov_b32_e32 v151, v1
	global_load_lds_dwordx4 v152, s[4:5]
	v_mov_b32_e32 v153, v1
	s_cmp_eq_u32 s7, 1
	v_lshl_add_u64 v[130:131], s[12:13], 0, v[0:1]
	v_lshl_add_u64 v[132:133], s[12:13], 0, v[154:155]
	v_lshl_add_u64 v[138:139], s[40:41], 0, v[150:151]
	v_lshl_add_u64 v[140:141], s[40:41], 0, v[152:153]
	s_cselect_b64 s[22:23], -1, 0
	s_cmp_lg_u32 s7, 1
	s_cbranch_scc1 .LBB0_190
	s_barrier

; #define PG8_STAGE(bufoff, gbase, voff) do { _Pragma("unroll") for (int _i = 0; _i < 2; ++_i) \
;         __builtin_amdgcn_global_load_lds((const unsigned*)((const char*)(gbase) + (voff)[_i]), (LAS unsigned*)(lds + (bufoff) + ldsw + _i * 8192), 16, 0, 0); } while (0)
; #define PG8_LDA(dst, b, h) do { _Pragma("unroll") for (int m = 0; m < 4; ++m) _Pragma("unroll") for (int k = 0; k < 2; ++k) dst[m][k] = *(const LAS bf16x8*)(lds + PG8_SA(b, h) + aoff + m * 2048 + k * 1024); } while (0)
; #define PG8_LDB(dst, b, h) do { _Pragma("unroll") for (int n = 0; n < 2; ++n) _Pragma("unroll") for (int k = 0; k < 2; ++k) dst[n][k] = *(const LAS bf16x8*)(lds + PG8_SB(b, h) + boff + n * 2048 + k * 1024); } while (0)
; #define PG8_MMA(ai, bj, At, Bt) do { __builtin_amdgcn_s_setprio(1); _Pragma("unroll") for (int m = 0; m < 4; ++m) _Pragma("unroll") for (int n = 0; n < 2; ++n) _Pragma("unroll") for (int k = 0; k < 2; ++k) \
;         acc[ai][bj][m][n] = __builtin_amdgcn_mfma_f32_16x16x32_bf16(Bt[n][k], At[m][k], acc[ai][bj][m][n], 0, 0, 0); __builtin_amdgcn_s_setprio(0); } while (0)
; #define PG8_WAIT_V(n) asm volatile("s_waitcnt vmcnt(" #n ")" ::: "memory")
; #define PG8_WAIT_L(n) asm volatile("s_waitcnt lgkmcnt(" #n ")" ::: "memory")
; #define PG8_BAR __builtin_amdgcn_s_barrier()
; #define PG8_SCHED __builtin_amdgcn_sched_barrier(0)
; template <class Epi>
; __device__ __forceinline__ void gemm_phase(LAS unsigned char* lds, const Gemm g, const Order& S, const Epi& E, const int tid) {
;     ...
;         for (int t = 0; t < nt; t += 2) {
;             const bool last = (t == nt - 2);
;             const char* a1 = cA + (size_t)(t + 1) * kstep;
;             const char* a2 = last ? nA : cA + (size_t)(t + 2) * kstep; const char* b2 = last ? nB : cB + (size_t)(t + 2) * kstep;
;             const char* a3 = a2 + kstep; const char* b3 = b2 + kstep;
;             PG8_LDB(B0, 0, 0); PG8_LDB(B1, 0, 1); PG8_SCHED; PG8_LDA(At, 0, 0); PG8_STAGE(PG8_SA(1, 1), a1 + hstep, voffA);
;             PG8_WAIT_V(8); PG8_WAIT_L(0); PG8_BAR; PG8_MMA(0, 0, At, B0); PG8_MMA(0, 1, At, B1); PG8_BAR; PG8_SCHED;
;             PG8_LDA(At, 0, 1); PG8_STAGE(PG8_SB(0, 0), b2, voffB); PG8_STAGE(PG8_SB(0, 1), b2 + hstep, voffB); PG8_STAGE(PG8_SA(0, 0), a2, voffA);
;             PG8_WAIT_V(8); PG8_WAIT_L(0); PG8_BAR; PG8_MMA(1, 0, At, B0); PG8_MMA(1, 1, At, B1); PG8_BAR; PG8_SCHED;
.LBB0_203:
	s_add_u32 s10, s40, 0x80
	s_addc_u32 s11, s41, 0
	s_add_u32 s40, s12, 0x100
	s_addc_u32 s41, s13, 0
	s_mov_b32 s12, 0
	s_add_i32 s56, s12, 2
	s_add_u32 s57, s10, 0x80
	s_addc_u32 s13, s11, 0
	s_add_i32 s60, 0, 0x10000
	s_cmp_eq_u32 s82, s12
	s_cselect_b32 s13, s39, s13
	s_cselect_b32 s12, s38, s57
	s_cselect_b32 s59, s81, s41
	s_cselect_b32 s58, s80, s40
	s_add_i32 s57, 0, 0x14000
	v_add_u32_e32 v142, s60, v168
	v_add_u32_e32 v164, s57, v168
	ds_read_b128 v[130:133], v142
	ds_read_b128 v[134:137], v142 offset:1024
	ds_read_b128 v[138:141], v142 offset:2048
	ds_read_b128 v[142:145], v142 offset:3072
	ds_read_b128 v[146:149], v164
	ds_read_b128 v[160:163], v164 offset:1024
	ds_read_b128 v[176:179], v164 offset:2048
	ds_read_b128 v[192:195], v164 offset:3072
	v_lshl_add_u64 v[164:165], s[10:11], 0, v[156:157]
	s_add_i32 m0, s51, 0xc000
	ds_read_b128 v[200:203], v175
	ds_read_b128 v[204:207], v175 offset:1024
	ds_read_b128 v[220:223], v175 offset:2048
	ds_read_b128 v[224:227], v175 offset:3072
	ds_read_b128 v[228:231], v175 offset:4096
	ds_read_b128 v[232:235], v175 offset:5120
	ds_read_b128 v[236:239], v175 offset:6144
	ds_read_b128 v[240:243], v175 offset:7168
	global_load_lds_dwordx4 v[164:165], off
	v_lshl_add_u64 v[164:165], s[10:11], 0, v[158:159]
	s_add_i32 m0, s51, 0xe000
	s_nop 0
	global_load_lds_dwordx4 v[164:165], off
	s_waitcnt vmcnt(8)
	s_waitcnt lgkmcnt(0)
	s_barrier
	s_setprio 1
	s_waitcnt lgkmcnt(0)
	v_mfma_f32_16x16x32_bf16 v[122:125], v[130:133], v[200:203], 0
	v_mfma_f32_16x16x32_bf16 v[126:129], v[138:141], v[200:203], 0
	v_mfma_f32_16x16x32_bf16 v[110:113], v[130:133], v[220:223], 0
	v_mfma_f32_16x16x32_bf16 v[106:109], v[138:141], v[220:223], 0
	v_mfma_f32_16x16x32_bf16 v[94:97], v[130:133], v[228:231], 0
	v_mfma_f32_16x16x32_bf16 v[90:93], v[138:141], v[228:231], 0
	v_mfma_f32_16x16x32_bf16 v[78:81], v[130:133], v[236:239], 0
	v_mfma_f32_16x16x32_bf16 v[74:77], v[138:141], v[236:239], 0
	v_mfma_f32_16x16x32_bf16 v[122:125], v[134:137], v[204:207], v[122:125]
	v_mfma_f32_16x16x32_bf16 v[126:129], v[142:145], v[204:207], v[126:129]
	v_mfma_f32_16x16x32_bf16 v[110:113], v[134:137], v[224:227], v[110:113]
	v_mfma_f32_16x16x32_bf16 v[106:109], v[142:145], v[224:227], v[106:109]
	v_mfma_f32_16x16x32_bf16 v[94:97], v[134:137], v[232:235], v[94:97]
	v_mfma_f32_16x16x32_bf16 v[90:93], v[142:145], v[232:235], v[90:93]
	v_mfma_f32_16x16x32_bf16 v[78:81], v[134:137], v[240:243], v[78:81]
	v_mfma_f32_16x16x32_bf16 v[74:77], v[142:145], v[240:243], v[74:77]
	s_setprio 0
	s_setprio 1
	v_mfma_f32_16x16x32_bf16 v[118:121], v[146:149], v[200:203], 0
	v_mfma_f32_16x16x32_bf16 v[114:117], v[176:179], v[200:203], 0
	v_mfma_f32_16x16x32_bf16 v[102:105], v[146:149], v[220:223], 0
	v_mfma_f32_16x16x32_bf16 v[98:101], v[176:179], v[220:223], 0
	v_mfma_f32_16x16x32_bf16 v[86:89], v[146:149], v[228:231], 0
	v_mfma_f32_16x16x32_bf16 v[82:85], v[176:179], v[228:231], 0
	v_mfma_f32_16x16x32_bf16 v[70:73], v[146:149], v[236:239], 0
	v_mfma_f32_16x16x32_bf16 v[66:69], v[176:179], v[236:239], 0
	v_mfma_f32_16x16x32_bf16 v[118:121], v[160:163], v[204:207], v[118:121]
	v_mfma_f32_16x16x32_bf16 v[114:117], v[192:195], v[204:207], v[114:117]
	v_mfma_f32_16x16x32_bf16 v[102:105], v[160:163], v[224:227], v[102:105]
	v_mfma_f32_16x16x32_bf16 v[98:101], v[192:195], v[224:227], v[98:101]
	v_mfma_f32_16x16x32_bf16 v[86:89], v[160:163], v[232:235], v[86:89]
	v_mfma_f32_16x16x32_bf16 v[82:85], v[192:195], v[232:235], v[82:85]
	v_mfma_f32_16x16x32_bf16 v[70:73], v[160:163], v[240:243], v[70:73]
	v_mfma_f32_16x16x32_bf16 v[66:69], v[192:195], v[240:243], v[66:69]
	s_setprio 0
	s_barrier
	s_add_i32 s60, s60, s48
	v_lshl_add_u64 v[164:165], s[58:59], 0, v[0:1]
	s_mov_b32 m0, s60
	ds_read_b128 v[200:203], v175 offset:16384
	ds_read_b128 v[204:207], v175 offset:17408
	ds_read_b128 v[220:223], v175 offset:18432
	ds_read_b128 v[224:227], v175 offset:19456
	ds_read_b128 v[228:231], v175 offset:20480
	ds_read_b128 v[232:235], v175 offset:21504
	ds_read_b128 v[236:239], v175 offset:22528
	ds_read_b128 v[240:243], v175 offset:23552
	global_load_lds_dwordx4 v[164:165], off
	s_add_i32 m0, s60, 0x2000
	v_lshl_add_u64 v[244:245], s[58:59], 0, v[154:155]
	s_add_u32 s58, s58, s76
	s_addc_u32 s59, s59, 0
	s_add_i32 s57, s57, s48
	global_load_lds_dwordx4 v[244:245], off
	v_lshl_add_u64 v[246:247], s[58:59], 0, v[0:1]
	s_mov_b32 m0, s57
	v_lshl_add_u64 v[248:249], s[58:59], 0, v[154:155]
	global_load_lds_dwordx4 v[246:247], off
	s_add_i32 m0, s57, 0x2000
	v_lshl_add_u64 v[250:251], s[12:13], 0, v[150:151]
	global_load_lds_dwordx4 v[248:249], off
	s_mov_b32 m0, s51
	v_lshl_add_u64 v[252:253], s[12:13], 0, v[152:153]
	global_load_lds_dwordx4 v[250:251], off
	s_mov_b32 m0, s52
	s_nop 0
	global_load_lds_dwordx4 v[252:253], off
	s_waitcnt vmcnt(8)
	s_waitcnt lgkmcnt(0)
	s_barrier
; #define PG8_STAGE(bufoff, gbase, voff) do { _Pragma("unroll") for (int _i = 0; _i < 2; ++_i) \
;         __builtin_amdgcn_global_load_lds((const unsigned*)((const char*)(gbase) + (voff)[_i]), (LAS unsigned*)(lds + (bufoff) + ldsw + _i * 8192), 16, 0, 0); } while (0)
; #define PG8_LDA(dst, b, h) do { _Pragma("unroll") for (int m = 0; m < 4; ++m) _Pragma("unroll") for (int k = 0; k < 2; ++k) dst[m][k] = *(const LAS bf16x8*)(lds + PG8_SA(b, h) + aoff + m * 2048 + k * 1024); } while (0)
; #define PG8_LDB(dst, b, h) do { _Pragma("unroll") for (int n = 0; n < 2; ++n) _Pragma("unroll") for (int k = 0; k < 2; ++k) dst[n][k] = *(const LAS bf16x8*)(lds + PG8_SB(b, h) + boff + n * 2048 + k * 1024); } while (0)
; #define PG8_MMA(ai, bj, At, Bt) do { __builtin_amdgcn_s_setprio(1); _Pragma("unroll") for (int m = 0; m < 4; ++m) _Pragma("unroll") for (int n = 0; n < 2; ++n) _Pragma("unroll") for (int k = 0; k < 2; ++k) \
;         acc[ai][bj][m][n] = __builtin_amdgcn_mfma_f32_16x16x32_bf16(Bt[n][k], At[m][k], acc[ai][bj][m][n], 0, 0, 0); __builtin_amdgcn_s_setprio(0); } while (0)
; #define PG8_WAIT_V(n) asm volatile("s_waitcnt vmcnt(" #n ")" ::: "memory")
; #define PG8_WAIT_L(n) asm volatile("s_waitcnt lgkmcnt(" #n ")" ::: "memory")
; #define PG8_BAR __builtin_amdgcn_s_barrier()
; #define PG8_SCHED __builtin_amdgcn_sched_barrier(0)
; template <class Epi>
; __device__ __forceinline__ void gemm_phase(LAS unsigned char* lds, const Gemm g, const Order& S, const Epi& E, const int tid) {
;     ...
;             PG8_WAIT_V(8); PG8_WAIT_L(0); PG8_BAR; PG8_MMA(1, 0, At, B0); PG8_MMA(1, 1, At, B1); PG8_BAR; PG8_SCHED;
;             PG8_LDB(B0, 1, 0); PG8_LDB(B1, 1, 1); PG8_SCHED; PG8_LDA(At, 1, 0); PG8_STAGE(PG8_SA(0, 1), a2 + hstep, voffA);
;             PG8_WAIT_V(8); PG8_WAIT_L(0); PG8_BAR; PG8_MMA(0, 0, At, B0); PG8_MMA(0, 1, At, B1); PG8_BAR; PG8_SCHED;
;             PG8_LDA(At, 1, 1); PG8_STAGE(PG8_SB(1, 0), b3, voffB); PG8_STAGE(PG8_SB(1, 1), b3 + hstep, voffB); PG8_STAGE(PG8_SA(1, 0), a3, voffA);
;             PG8_WAIT_V(8); PG8_WAIT_L(0); PG8_BAR; PG8_MMA(1, 0, At, B0); PG8_MMA(1, 1, At, B1); PG8_BAR; PG8_SCHED;
	s_setprio 1
	s_waitcnt lgkmcnt(0)
	v_mfma_f32_16x16x32_bf16 v[62:65], v[130:133], v[200:203], 0
	v_mfma_f32_16x16x32_bf16 v[58:61], v[138:141], v[200:203], 0
	v_mfma_f32_16x16x32_bf16 v[46:49], v[130:133], v[220:223], 0
	v_mfma_f32_16x16x32_bf16 v[42:45], v[138:141], v[220:223], 0
	v_mfma_f32_16x16x32_bf16 v[30:33], v[130:133], v[228:231], 0
	v_mfma_f32_16x16x32_bf16 v[26:29], v[138:141], v[228:231], 0
	v_mfma_f32_16x16x32_bf16 v[14:17], v[130:133], v[236:239], 0
	v_mfma_f32_16x16x32_bf16 v[10:13], v[138:141], v[236:239], 0
	v_mfma_f32_16x16x32_bf16 v[62:65], v[134:137], v[204:207], v[62:65]
	v_mfma_f32_16x16x32_bf16 v[58:61], v[142:145], v[204:207], v[58:61]
	v_mfma_f32_16x16x32_bf16 v[46:49], v[134:137], v[224:227], v[46:49]
	v_mfma_f32_16x16x32_bf16 v[42:45], v[142:145], v[224:227], v[42:45]
	v_mfma_f32_16x16x32_bf16 v[30:33], v[134:137], v[232:235], v[30:33]
	v_mfma_f32_16x16x32_bf16 v[26:29], v[142:145], v[232:235], v[26:29]
	v_mfma_f32_16x16x32_bf16 v[14:17], v[134:137], v[240:243], v[14:17]
	v_mfma_f32_16x16x32_bf16 v[10:13], v[142:145], v[240:243], v[10:13]
	s_setprio 0
	s_setprio 1
	v_mfma_f32_16x16x32_bf16 v[54:57], v[146:149], v[200:203], 0
	v_mfma_f32_16x16x32_bf16 v[50:53], v[176:179], v[200:203], 0
	v_mfma_f32_16x16x32_bf16 v[38:41], v[146:149], v[220:223], 0
	v_mfma_f32_16x16x32_bf16 v[34:37], v[176:179], v[220:223], 0
	v_mfma_f32_16x16x32_bf16 v[22:25], v[146:149], v[228:231], 0
	v_mfma_f32_16x16x32_bf16 v[18:21], v[176:179], v[228:231], 0
	v_mfma_f32_16x16x32_bf16 v[6:9], v[146:149], v[236:239], 0
	v_mfma_f32_16x16x32_bf16 v[2:5], v[176:179], v[236:239], 0
	v_mfma_f32_16x16x32_bf16 v[54:57], v[160:163], v[204:207], v[54:57]
	v_mfma_f32_16x16x32_bf16 v[50:53], v[192:195], v[204:207], v[50:53]
	v_mfma_f32_16x16x32_bf16 v[38:41], v[160:163], v[224:227], v[38:41]
	v_mfma_f32_16x16x32_bf16 v[34:37], v[192:195], v[224:227], v[34:37]
	v_mfma_f32_16x16x32_bf16 v[22:25], v[160:163], v[232:235], v[22:25]
	v_mfma_f32_16x16x32_bf16 v[18:21], v[192:195], v[232:235], v[18:21]
	v_mfma_f32_16x16x32_bf16 v[6:9], v[160:163], v[240:243], v[6:9]
	v_mfma_f32_16x16x32_bf16 v[2:5], v[192:195], v[240:243], v[2:5]
	s_setprio 0
	s_barrier
	s_add_i32 s57, 0, 0x18000
	s_add_i32 s58, 0, 0x1c000
	v_add_u32_e32 v142, s57, v168
	v_add_u32_e32 v192, s58, v168
	ds_read_b128 v[130:133], v142
	ds_read_b128 v[134:137], v142 offset:1024
	ds_read_b128 v[138:141], v142 offset:2048
	ds_read_b128 v[142:145], v142 offset:3072
	ds_read_b128 v[146:149], v192
	ds_read_b128 v[160:163], v192 offset:1024
	ds_read_b128 v[176:179], v192 offset:2048
	ds_read_b128 v[192:195], v192 offset:3072
	s_add_u32 s12, s12, s76
	s_addc_u32 s13, s13, 0
	s_mov_b32 m0, s53
	v_lshl_add_u64 v[198:199], s[12:13], 0, v[150:151]
	ds_read_b128 v[200:203], v175 offset:32768
	ds_read_b128 v[204:207], v175 offset:33792
	ds_read_b128 v[220:223], v175 offset:34816
	ds_read_b128 v[224:227], v175 offset:35840
	ds_read_b128 v[228:231], v175 offset:36864
	ds_read_b128 v[232:235], v175 offset:37888
	ds_read_b128 v[236:239], v175 offset:38912
	ds_read_b128 v[240:243], v175 offset:39936
	global_load_lds_dwordx4 v[198:199], off
	v_lshl_add_u64 v[198:199], s[12:13], 0, v[152:153]
	s_mov_b32 m0, s54
	s_nop 0
	global_load_lds_dwordx4 v[198:199], off
	s_waitcnt vmcnt(8)
	s_waitcnt lgkmcnt(0)
	s_barrier
	s_setprio 1
	s_waitcnt lgkmcnt(0)
	v_mfma_f32_16x16x32_bf16 v[122:125], v[130:133], v[200:203], v[122:125]
	v_mfma_f32_16x16x32_bf16 v[126:129], v[138:141], v[200:203], v[126:129]
	v_mfma_f32_16x16x32_bf16 v[110:113], v[130:133], v[220:223], v[110:113]
	v_mfma_f32_16x16x32_bf16 v[106:109], v[138:141], v[220:223], v[106:109]
	v_mfma_f32_16x16x32_bf16 v[94:97], v[130:133], v[228:231], v[94:97]
	v_mfma_f32_16x16x32_bf16 v[90:93], v[138:141], v[228:231], v[90:93]
	v_mfma_f32_16x16x32_bf16 v[78:81], v[130:133], v[236:239], v[78:81]
	v_mfma_f32_16x16x32_bf16 v[74:77], v[138:141], v[236:239], v[74:77]
	v_mfma_f32_16x16x32_bf16 v[122:125], v[134:137], v[204:207], v[122:125]
	v_mfma_f32_16x16x32_bf16 v[126:129], v[142:145], v[204:207], v[126:129]
	v_mfma_f32_16x16x32_bf16 v[110:113], v[134:137], v[224:227], v[110:113]
	v_mfma_f32_16x16x32_bf16 v[106:109], v[142:145], v[224:227], v[106:109]
	v_mfma_f32_16x16x32_bf16 v[94:97], v[134:137], v[232:235], v[94:97]
	v_mfma_f32_16x16x32_bf16 v[90:93], v[142:145], v[232:235], v[90:93]
	v_mfma_f32_16x16x32_bf16 v[78:81], v[134:137], v[240:243], v[78:81]
	v_mfma_f32_16x16x32_bf16 v[74:77], v[142:145], v[240:243], v[74:77]
	s_setprio 0
	s_setprio 1
	v_mfma_f32_16x16x32_bf16 v[118:121], v[146:149], v[200:203], v[118:121]
	v_mfma_f32_16x16x32_bf16 v[114:117], v[176:179], v[200:203], v[114:117]
	v_mfma_f32_16x16x32_bf16 v[102:105], v[146:149], v[220:223], v[102:105]
	v_mfma_f32_16x16x32_bf16 v[98:101], v[176:179], v[220:223], v[98:101]
	v_mfma_f32_16x16x32_bf16 v[86:89], v[146:149], v[228:231], v[86:89]
	v_mfma_f32_16x16x32_bf16 v[82:85], v[176:179], v[228:231], v[82:85]
	v_mfma_f32_16x16x32_bf16 v[70:73], v[146:149], v[236:239], v[70:73]
	v_mfma_f32_16x16x32_bf16 v[66:69], v[176:179], v[236:239], v[66:69]
	v_mfma_f32_16x16x32_bf16 v[118:121], v[160:163], v[204:207], v[118:121]
	v_mfma_f32_16x16x32_bf16 v[114:117], v[192:195], v[204:207], v[114:117]
	v_mfma_f32_16x16x32_bf16 v[102:105], v[160:163], v[224:227], v[102:105]
	v_mfma_f32_16x16x32_bf16 v[98:101], v[192:195], v[224:227], v[98:101]
	v_mfma_f32_16x16x32_bf16 v[86:89], v[160:163], v[232:235], v[86:89]
	v_mfma_f32_16x16x32_bf16 v[82:85], v[192:195], v[232:235], v[82:85]
	v_mfma_f32_16x16x32_bf16 v[70:73], v[160:163], v[240:243], v[70:73]
	v_mfma_f32_16x16x32_bf16 v[66:69], v[192:195], v[240:243], v[66:69]
	s_setprio 0
	s_barrier
; #define PG8_STAGE(bufoff, gbase, voff) do { _Pragma("unroll") for (int _i = 0; _i < 2; ++_i) \
;         __builtin_amdgcn_global_load_lds((const unsigned*)((const char*)(gbase) + (voff)[_i]), (LAS unsigned*)(lds + (bufoff) + ldsw + _i * 8192), 16, 0, 0); } while (0)
; #define PG8_LDA(dst, b, h) do { _Pragma("unroll") for (int m = 0; m < 4; ++m) _Pragma("unroll") for (int k = 0; k < 2; ++k) dst[m][k] = *(const LAS bf16x8*)(lds + PG8_SA(b, h) + aoff + m * 2048 + k * 1024); } while (0)
; #define PG8_MMA(ai, bj, At, Bt) do { __builtin_amdgcn_s_setprio(1); _Pragma("unroll") for (int m = 0; m < 4; ++m) _Pragma("unroll") for (int n = 0; n < 2; ++n) _Pragma("unroll") for (int k = 0; k < 2; ++k) \
;         acc[ai][bj][m][n] = __builtin_amdgcn_mfma_f32_16x16x32_bf16(Bt[n][k], At[m][k], acc[ai][bj][m][n], 0, 0, 0); __builtin_amdgcn_s_setprio(0); } while (0)
; #define PG8_WAIT_V(n) asm volatile("s_waitcnt vmcnt(" #n ")" ::: "memory")
; #define PG8_WAIT_L(n) asm volatile("s_waitcnt lgkmcnt(" #n ")" ::: "memory")
; #define PG8_BAR __builtin_amdgcn_s_barrier()
; #define PG8_SCHED __builtin_amdgcn_sched_barrier(0)
; template <class Epi>
; __device__ __forceinline__ void gemm_phase(LAS unsigned char* lds, const Gemm g, const Order& S, const Epi& E, const int tid) {
;     ...
;             PG8_LDA(At, 1, 1); PG8_STAGE(PG8_SB(1, 0), b3, voffB); PG8_STAGE(PG8_SB(1, 1), b3 + hstep, voffB); PG8_STAGE(PG8_SA(1, 0), a3, voffA);
;             PG8_WAIT_V(8); PG8_WAIT_L(0); PG8_BAR; PG8_MMA(1, 0, At, B0); PG8_MMA(1, 1, At, B1); PG8_BAR; PG8_SCHED;
;         }
	s_add_i32 s12, s57, s48
	v_lshl_add_u64 v[164:165], v[164:165], 0, s[86:87]
	s_mov_b32 m0, s12
	ds_read_b128 v[200:203], v175 offset:49152
	ds_read_b128 v[204:207], v175 offset:50176
	ds_read_b128 v[220:223], v175 offset:51200
	ds_read_b128 v[224:227], v175 offset:52224
	ds_read_b128 v[228:231], v175 offset:53248
	ds_read_b128 v[232:235], v175 offset:54272
	ds_read_b128 v[236:239], v175 offset:55296
	ds_read_b128 v[240:243], v175 offset:56320
	global_load_lds_dwordx4 v[164:165], off
	v_lshl_add_u64 v[164:165], v[244:245], 0, s[86:87]
	s_add_i32 m0, s12, 0x2000
	s_add_i32 s12, s58, s48
	global_load_lds_dwordx4 v[164:165], off
	v_lshl_add_u64 v[164:165], v[246:247], 0, s[86:87]
	s_mov_b32 m0, s12
	s_nop 0
	global_load_lds_dwordx4 v[164:165], off
	v_lshl_add_u64 v[164:165], v[248:249], 0, s[86:87]
	s_add_i32 m0, s12, 0x2000
	s_nop 0
	global_load_lds_dwordx4 v[164:165], off
	v_lshl_add_u64 v[164:165], v[250:251], 0, s[86:87]
	s_mov_b32 m0, s55
	s_nop 0
	global_load_lds_dwordx4 v[164:165], off
	v_lshl_add_u64 v[164:165], v[252:253], 0, s[86:87]
	s_mov_b32 m0, s74
	s_nop 0
	global_load_lds_dwordx4 v[164:165], off
	s_waitcnt vmcnt(8)
	s_waitcnt lgkmcnt(0)
	s_barrier
	s_setprio 1
	s_waitcnt lgkmcnt(0)
	v_mfma_f32_16x16x32_bf16 v[62:65], v[130:133], v[200:203], v[62:65]
	v_mfma_f32_16x16x32_bf16 v[58:61], v[138:141], v[200:203], v[58:61]
	v_mfma_f32_16x16x32_bf16 v[46:49], v[130:133], v[220:223], v[46:49]
	v_mfma_f32_16x16x32_bf16 v[42:45], v[138:141], v[220:223], v[42:45]
	v_mfma_f32_16x16x32_bf16 v[30:33], v[130:133], v[228:231], v[30:33]
	v_mfma_f32_16x16x32_bf16 v[26:29], v[138:141], v[228:231], v[26:29]
	v_mfma_f32_16x16x32_bf16 v[14:17], v[130:133], v[236:239], v[14:17]
	v_mfma_f32_16x16x32_bf16 v[10:13], v[138:141], v[236:239], v[10:13]
	v_mfma_f32_16x16x32_bf16 v[62:65], v[134:137], v[204:207], v[62:65]
	v_mfma_f32_16x16x32_bf16 v[58:61], v[142:145], v[204:207], v[58:61]
	v_mfma_f32_16x16x32_bf16 v[46:49], v[134:137], v[224:227], v[46:49]
	v_mfma_f32_16x16x32_bf16 v[42:45], v[142:145], v[224:227], v[42:45]
	v_mfma_f32_16x16x32_bf16 v[30:33], v[134:137], v[232:235], v[30:33]
	v_mfma_f32_16x16x32_bf16 v[26:29], v[142:145], v[232:235], v[26:29]
	v_mfma_f32_16x16x32_bf16 v[14:17], v[134:137], v[240:243], v[14:17]
	v_mfma_f32_16x16x32_bf16 v[10:13], v[142:145], v[240:243], v[10:13]
	s_setprio 0
	s_setprio 1
	v_mfma_f32_16x16x32_bf16 v[54:57], v[146:149], v[200:203], v[54:57]
	v_mfma_f32_16x16x32_bf16 v[50:53], v[176:179], v[200:203], v[50:53]
	v_mfma_f32_16x16x32_bf16 v[38:41], v[146:149], v[220:223], v[38:41]
	v_mfma_f32_16x16x32_bf16 v[34:37], v[176:179], v[220:223], v[34:37]
	v_mfma_f32_16x16x32_bf16 v[22:25], v[146:149], v[228:231], v[22:25]
	v_mfma_f32_16x16x32_bf16 v[18:21], v[176:179], v[228:231], v[18:21]
	v_mfma_f32_16x16x32_bf16 v[6:9], v[146:149], v[236:239], v[6:9]
	v_mfma_f32_16x16x32_bf16 v[2:5], v[176:179], v[236:239], v[2:5]
	v_mfma_f32_16x16x32_bf16 v[54:57], v[160:163], v[204:207], v[54:57]
	v_mfma_f32_16x16x32_bf16 v[50:53], v[192:195], v[204:207], v[50:53]
	v_mfma_f32_16x16x32_bf16 v[38:41], v[160:163], v[224:227], v[38:41]
	v_mfma_f32_16x16x32_bf16 v[34:37], v[192:195], v[224:227], v[34:37]
	v_mfma_f32_16x16x32_bf16 v[22:25], v[160:163], v[232:235], v[22:25]
	v_mfma_f32_16x16x32_bf16 v[18:21], v[192:195], v[232:235], v[18:21]
	v_mfma_f32_16x16x32_bf16 v[6:9], v[160:163], v[240:243], v[6:9]
	v_mfma_f32_16x16x32_bf16 v[2:5], v[192:195], v[240:243], v[2:5]
	s_setprio 0
	s_barrier
	s_add_u32 s10, s10, 0x100
	s_addc_u32 s11, s11, 0
	s_add_u32 s40, s40, 0x100
	s_addc_u32 s41, s41, 0
	s_cmp_ge_u32 s56, s79
	s_mov_b32 s12, s56

; #define PG8_BAR __builtin_amdgcn_s_barrier()
; template <class Epi>
; __device__ __forceinline__ void gemm_phase(LAS unsigned char* lds, const Gemm g, const Order& S, const Epi& E, const int tid) {
;     ...
;         if (!has_next) break;
; #pragma unroll
;         for (int a = 0; a < 2; ++a)
; #pragma unroll
;             for (int b = 0; b < 2; ++b)
; #pragma unroll
;                 for (int m = 0; m < 4; ++m)
; #pragma unroll
;                     for (int n = 0; n < 2; ++n) { double zl, zh; asm volatile("v_mov_b64 %0, 0\n\tv_mov_b64 %1, 0" : "=v"(zl), "=v"(zh)); d64x2 zz = {zl, zh}; acc[a][b][m][n] = __builtin_bit_cast(f32x4, zz); }
;         cur = nxt; cA = nA; cB = nB; ++ui;
;         if (wr == 1) PG8_BAR;
.LBB0_306:
	s_andn2_b64 vcc, exec, s[22:23]
	s_cbranch_vccnz .LBB0_191
	s_barrier
	s_branch .LBB0_191

; #define PG8_STAGE(bufoff, gbase, voff) do { _Pragma("unroll") for (int _i = 0; _i < 2; ++_i) \
;         __builtin_amdgcn_global_load_lds((const unsigned*)((const char*)(gbase) + (voff)[_i]), (LAS unsigned*)(lds + (bufoff) + ldsw + _i * 8192), 16, 0, 0); } while (0)
; #define PG8_WAIT_V(n) asm volatile("s_waitcnt vmcnt(" #n ")" ::: "memory")
; #define PG8_BAR __builtin_amdgcn_s_barrier()
; __device__ __forceinline__ float row_rstd(const float* ssq, int row) {
;     const f32x4 s = *(const f32x4*)(ssq + (size_t)row * 4);
;     return rsqrtf(((s.x + s.y) + (s.z + s.w)) * (1.f / DM) + EPS);
; template <class Epi>
; __device__ __forceinline__ void gemm_phase(LAS unsigned char* lds, const Gemm g, const Order& S, const Epi& E, const int tid) {
;     ...
;     PG8_STAGE(PG8_SB(0, 0), cB, voffB); PG8_STAGE(PG8_SB(0, 1), cB + hstep, voffB); PG8_STAGE(PG8_SA(0, 0), cA, voffA); PG8_STAGE(PG8_SA(0, 1), cA + hstep, voffA);
;     if (wr == 1) PG8_BAR;
;     PG8_WAIT_V(2); PG8_BAR;
;     PG8_STAGE(PG8_SB(1, 0), cB + kstep, voffB); PG8_STAGE(PG8_SA(1, 0), cA + kstep, voffA); PG8_STAGE(PG8_SB(1, 1), cB + hstep + kstep, voffB);
;     PG8_WAIT_V(6); PG8_BAR;
.LBB0_313:
	s_waitcnt vmcnt(0)
	v_mov_b32_e32 v144, v130
	v_mov_b32_e32 v145, v134
	v_mov_b32_e32 v134, v131
	v_pk_add_f32 v[130:131], v[144:145], v[134:135]
	v_mov_b32_e32 v134, v132
	v_mov_b32_e32 v135, v136
	v_mov_b32_e32 v136, v133
	v_pk_add_f32 v[132:133], v[134:135], v[136:137]
	s_sext_i32_i16 s7, s4
	v_pk_add_f32 v[130:131], v[130:131], v[132:133]
	v_or_b32_e32 v155, s11, v154
	v_pk_fma_f32 v[130:131], v[130:131], s[84:85], v[182:183] op_sel_hi:[1,0,0]
	v_mov_b32_e32 v252, v130
	v_mov_b32_e32 v253, v131
	s_add_i32 m0, s37, 0x18000
	v_mul_f32_e32 v132, 0x4b800000, v130
	v_cmp_gt_f32_e64 s[4:5], s89, v130
	v_cmp_gt_f32_e32 vcc, s89, v131
	s_waitcnt vmcnt(2)
	s_barrier
	v_cndmask_b32_e64 v130, v130, v132, s[4:5]
	v_mul_f32_e32 v132, 0x4b800000, v131
	v_cndmask_b32_e32 v131, v131, v132, vcc
	v_rsq_f32_e32 v130, v130
	v_rsq_f32_e32 v131, v131
	s_add_i32 s41, s37, 0x8000
	s_add_i32 s42, s37, 0xa000
	s_mov_b32 s47, 0
	v_pk_mul_f32 v[132:133], v[130:131], s[78:79] op_sel_hi:[1,0]
	s_nop 0
	v_cndmask_b32_e32 v145, v131, v133, vcc
	v_cndmask_b32_e64 v144, v130, v132, s[4:5]
	v_lshlrev_b32_e32 v130, 6, v155
	s_movk_i32 s4, 0x3c0
	v_lshlrev_b32_e32 v131, 2, v155
	v_and_or_b32 v130, v130, s4, v160
	s_lshl_b32 s4, s10, 13
	v_and_b32_e32 v131, 32, v131
	v_bitop3_b32 v132, v130, s4, v131 bitop3:0xde
	s_lshl_b32 s4, s9, 5
	s_and_b32 s10, s4, 0x60
	v_lshlrev_b32_e32 v131, 2, v154
	v_lshl_or_b32 v130, v154, 6, v160
	s_lshl_b32 s4, s10, 7
	v_and_b32_e32 v131, 32, v131
	v_bitop3_b32 v156, s4, v130, v131 bitop3:0xf6
	v_lshl_add_u64 v[130:131], v[152:153], 0, s[86:87]
	global_load_lds_dwordx4 v[130:131], off
	v_lshl_add_u64 v[130:131], v[150:151], 0, s[86:87]
	s_add_i32 m0, s37, 0x1a000
	s_add_u32 s4, s22, 0x40080
	global_load_lds_dwordx4 v[130:131], off
	v_lshl_add_u64 v[130:131], v[148:149], 0, s[86:87]
	s_mov_b32 m0, s41
	s_addc_u32 s5, s23, 0
	global_load_lds_dwordx4 v[130:131], off
	v_lshl_add_u64 v[130:131], v[146:147], 0, s[86:87]
	s_mov_b32 m0, s42
	v_or_b32_e32 v150, v155, v160
	global_load_lds_dwordx4 v[130:131], off
	s_add_i32 m0, s37, 0x1c000
	v_lshl_add_u64 v[130:131], s[4:5], 0, v[0:1]
	global_load_lds_dwordx4 v[130:131], off
	v_lshl_add_u64 v[130:131], s[4:5], 0, v[138:139]
	s_add_i32 m0, s37, 0x1e000
	s_cmpk_lt_u32 s8, 0x100
	global_load_lds_dwordx4 v[130:131], off
	v_lshlrev_b32_e32 v130, 14, v163
	v_and_b32_e32 v130, 0xffff8000, v130
	v_lshl_add_u32 v130, v162, 11, v130
	v_and_b32_e32 v131, 1, v163
	v_lshl_or_b32 v130, v131, 6, v130
	v_lshl_add_u32 v146, v164, 1, v130
	v_lshlrev_b32_e32 v130, 14, v157
	v_and_b32_e32 v130, 0xffff8000, v130
	s_waitcnt vmcnt(6)
	v_lshl_add_u32 v130, v159, 11, v130
	v_and_b32_e32 v131, 1, v157
	v_lshl_or_b32 v130, v131, 6, v130
	s_cselect_b64 s[8:9], -1, 0
	s_ashr_i32 s43, s44, 31
	v_lshl_or_b32 v151, v158, 3, s10
	v_mov_b32_e32 v147, v1
	v_lshl_add_u32 v148, v161, 1, v130
	v_mov_b32_e32 v149, v1
	v_add_u32_e32 v152, 0, v132
	s_barrier
	s_branch .LBB0_316

; __device__ __forceinline__ unsigned pk_bf16(float lo, float hi) { f32x2 v = {lo, hi}; bf16x2_t b = __builtin_convertvector(v, bf16x2_t); return __builtin_bit_cast(unsigned, b); }
; __device__ __forceinline__ float fast_exp2(float x) { return __builtin_amdgcn_exp2f(x); }
; __device__ __forceinline__ float fast_rcp(float x) { return __builtin_amdgcn_rcpf(x); }
;     __device__ __forceinline__ void operator()(const f32x4 (&acc)[2][2][4][2], const Unit& u, int wr, int wc, int fr, int fq, float rp0, float rp1, const f32x4& raw0, const f32x4& raw1, float& rn0, float& rn1) const {
;         const int row0 = u.pm * BM + wr * 64 + fr, col0 = u.pn * 128 + wc * 32 + 8 * fq;
;         float rs[8];
; #pragma unroll
;         for (int k = 0; k < 8; ++k) rs[k] = __shfl((k >> 2) ? rp1 : rp0, fr + 16 * (k & 3));
; #pragma unroll
;         for (int ai = 0; ai < 2; ++ai)
; #pragma unroll
;             for (int m = 0; m < 4; ++m) {
;                 const int row = row0 + ai * HALF + m * 16; const float r = rs[ai * 4 + m];
;                 const float c1 = -1.4426950408889634f * r, r2 = r * r;
;                 const f32x4 ga = acc[ai][0][m][0], gb = acc[ai][0][m][1];
;                 const f32x4 ta = ga * c1, tb = gb * c1;
;                 f32x4 ea, eb;
; #pragma unroll
;                 for (int j = 0; j < 4; ++j) { ea[j] = fast_exp2(ta[j]); eb[j] = fast_exp2(tb[j]); }
;                 const f32x4 da = ea + 1.f, db = eb + 1.f;
;                 f32x4 qa, qb;
; #pragma unroll
;                 for (int j = 0; j < 4; ++j) { qa[j] = fast_rcp(da[j]); qb[j] = fast_rcp(db[j]); }
;                 const f32x4 oa = ((ga * acc[ai][1][m][0]) * r2) * qa, ob = ((gb * acc[ai][1][m][1]) * r2) * qb;
;                 u32x4 w;
;                 w.x = pk_bf16(oa[0], oa[1]); w.y = pk_bf16(oa[2], oa[3]); w.z = pk_bf16(ob[0], ob[1]); w.w = pk_bf16(ob[2], ob[3]);
;                 if (ai == 0 && m == 0) rstd_finish(raw0, raw1, rn0, rn1);
;                 *(u32x4*)(O + (size_t)row * FF + col0) = w;
.LBB0_322:
	s_andn2_b64 vcc, exec, s[4:5]
	s_mov_b64 s[4:5], -1
	v_and_or_b32 v157, v197, 64, v154
	v_lshlrev_b32_e32 v157, 2, v157
	ds_bpermute_b32 v162, v157, v144
	ds_bpermute_b32 v163, v157, v144 offset:64
	ds_bpermute_b32 v164, v157, v144 offset:128
	ds_bpermute_b32 v165, v157, v144 offset:192
	ds_bpermute_b32 v166, v157, v145
	ds_bpermute_b32 v167, v157, v145 offset:64
	ds_bpermute_b32 v168, v157, v145 offset:128
	ds_bpermute_b32 v169, v157, v145 offset:192
	ds_bpermute_b32 v200, v157, v252
	ds_bpermute_b32 v202, v157, v252 offset:64
	ds_bpermute_b32 v204, v157, v252 offset:128
	ds_bpermute_b32 v206, v157, v252 offset:192
	ds_bpermute_b32 v220, v157, v253
	ds_bpermute_b32 v222, v157, v253 offset:64
	ds_bpermute_b32 v224, v157, v253 offset:128
	ds_bpermute_b32 v226, v157, v253 offset:192
	v_lshl_add_u32 v153, s6, 8, v155
	v_lshl_or_b32 v160, s7, 7, v151
	v_mul_u32_u24_e32 v161, 0x1600, v153
	v_lshl_add_u32 v161, v160, 1, v161
	s_waitcnt lgkmcnt(0)
	v_mul_f32_e32 v228, 0xbfb8aa3b, v162
	v_pk_mul_f32 v[126:127], v[118:119], v[126:127]
	v_pk_mul_f32 v[128:129], v[120:121], v[128:129]
	v_pk_mul_f32 v[122:123], v[114:115], v[122:123]
	v_pk_mul_f32 v[124:125], v[116:117], v[124:125]
	v_pk_mul_f32 v[118:119], v[118:119], v[228:229] op_sel_hi:[1,0]
	v_pk_mul_f32 v[120:121], v[120:121], v[228:229] op_sel_hi:[1,0]
	v_pk_mul_f32 v[114:115], v[114:115], v[228:229] op_sel_hi:[1,0]
	v_pk_mul_f32 v[116:117], v[116:117], v[228:229] op_sel_hi:[1,0]
	v_exp_f32_e32 v118, v118
	v_exp_f32_e32 v119, v119
	v_exp_f32_e32 v120, v120
	v_exp_f32_e32 v121, v121
	v_exp_f32_e32 v114, v114
	v_exp_f32_e32 v115, v115
	v_exp_f32_e32 v116, v116
	v_exp_f32_e32 v117, v117
	v_pk_fma_f32 v[118:119], v[118:119], v[200:201], v[200:201] op_sel_hi:[1,0,0]
	v_pk_fma_f32 v[120:121], v[120:121], v[200:201], v[200:201] op_sel_hi:[1,0,0]
	v_pk_fma_f32 v[114:115], v[114:115], v[200:201], v[200:201] op_sel_hi:[1,0,0]
	v_pk_fma_f32 v[116:117], v[116:117], v[200:201], v[200:201] op_sel_hi:[1,0,0]
	v_rcp_f32_e32 v118, v118
	v_rcp_f32_e32 v119, v119
	v_rcp_f32_e32 v120, v120
	v_rcp_f32_e32 v121, v121
	v_rcp_f32_e32 v114, v114
	v_rcp_f32_e32 v115, v115
	v_rcp_f32_e32 v116, v116
	v_rcp_f32_e32 v117, v117
	v_pk_mul_f32 v[126:127], v[126:127], v[118:119]
	v_pk_mul_f32 v[128:129], v[128:129], v[120:121]
	v_pk_mul_f32 v[122:123], v[122:123], v[114:115]
	v_pk_mul_f32 v[124:125], v[124:125], v[116:117]
	v_cvt_pk_bf16_f32 v118, v126, v127
	v_cvt_pk_bf16_f32 v119, v128, v129
	v_cvt_pk_bf16_f32 v120, v122, v123
	v_cvt_pk_bf16_f32 v121, v124, v125
	global_store_dwordx4 v161, v[118:121], s[24:25]
	v_mul_f32_e32 v228, 0xbfb8aa3b, v163
	v_pk_mul_f32 v[110:111], v[102:103], v[110:111]
	v_pk_mul_f32 v[112:113], v[104:105], v[112:113]
	v_pk_mul_f32 v[106:107], v[98:99], v[106:107]
	v_pk_mul_f32 v[108:109], v[100:101], v[108:109]
	v_pk_mul_f32 v[102:103], v[102:103], v[228:229] op_sel_hi:[1,0]
	v_pk_mul_f32 v[104:105], v[104:105], v[228:229] op_sel_hi:[1,0]
	v_pk_mul_f32 v[98:99], v[98:99], v[228:229] op_sel_hi:[1,0]
	v_pk_mul_f32 v[100:101], v[100:101], v[228:229] op_sel_hi:[1,0]
	v_exp_f32_e32 v102, v102
	v_exp_f32_e32 v103, v103
	v_exp_f32_e32 v104, v104
	v_exp_f32_e32 v105, v105
	v_exp_f32_e32 v98, v98
	v_exp_f32_e32 v99, v99
	v_exp_f32_e32 v100, v100
	v_exp_f32_e32 v101, v101
	v_pk_fma_f32 v[102:103], v[102:103], v[202:203], v[202:203] op_sel_hi:[1,0,0]
	v_pk_fma_f32 v[104:105], v[104:105], v[202:203], v[202:203] op_sel_hi:[1,0,0]
	v_pk_fma_f32 v[98:99], v[98:99], v[202:203], v[202:203] op_sel_hi:[1,0,0]
	v_pk_fma_f32 v[100:101], v[100:101], v[202:203], v[202:203] op_sel_hi:[1,0,0]
	v_rcp_f32_e32 v102, v102
	v_rcp_f32_e32 v103, v103
	v_rcp_f32_e32 v104, v104
	v_rcp_f32_e32 v105, v105
	v_rcp_f32_e32 v98, v98
	v_rcp_f32_e32 v99, v99
	v_rcp_f32_e32 v100, v100
	v_rcp_f32_e32 v101, v101
	v_pk_mul_f32 v[110:111], v[110:111], v[102:103]
	v_pk_mul_f32 v[112:113], v[112:113], v[104:105]
	v_pk_mul_f32 v[106:107], v[106:107], v[98:99]
	v_pk_mul_f32 v[108:109], v[108:109], v[100:101]
	v_cvt_pk_bf16_f32 v102, v110, v111
	v_cvt_pk_bf16_f32 v103, v112, v113
	v_cvt_pk_bf16_f32 v104, v106, v107
	v_cvt_pk_bf16_f32 v105, v108, v109
	v_add_u32_e32 v170, 0x16000, v161
	global_store_dwordx4 v170, v[102:105], s[24:25]
	v_mul_f32_e32 v228, 0xbfb8aa3b, v164
	v_pk_mul_f32 v[94:95], v[86:87], v[94:95]
	v_pk_mul_f32 v[96:97], v[88:89], v[96:97]
	v_pk_mul_f32 v[90:91], v[82:83], v[90:91]
	v_pk_mul_f32 v[92:93], v[84:85], v[92:93]
	v_pk_mul_f32 v[86:87], v[86:87], v[228:229] op_sel_hi:[1,0]
	v_pk_mul_f32 v[88:89], v[88:89], v[228:229] op_sel_hi:[1,0]
	v_pk_mul_f32 v[82:83], v[82:83], v[228:229] op_sel_hi:[1,0]
	v_pk_mul_f32 v[84:85], v[84:85], v[228:229] op_sel_hi:[1,0]
	v_exp_f32_e32 v86, v86
	v_exp_f32_e32 v87, v87
	v_exp_f32_e32 v88, v88
	v_exp_f32_e32 v89, v89
	v_exp_f32_e32 v82, v82
	v_exp_f32_e32 v83, v83
	v_exp_f32_e32 v84, v84
	v_exp_f32_e32 v85, v85
	v_pk_fma_f32 v[86:87], v[86:87], v[204:205], v[204:205] op_sel_hi:[1,0,0]
	v_pk_fma_f32 v[88:89], v[88:89], v[204:205], v[204:205] op_sel_hi:[1,0,0]
	v_pk_fma_f32 v[82:83], v[82:83], v[204:205], v[204:205] op_sel_hi:[1,0,0]
	v_pk_fma_f32 v[84:85], v[84:85], v[204:205], v[204:205] op_sel_hi:[1,0,0]
	v_rcp_f32_e32 v86, v86
	v_rcp_f32_e32 v87, v87
	v_rcp_f32_e32 v88, v88
	v_rcp_f32_e32 v89, v89
	v_rcp_f32_e32 v82, v82
	v_rcp_f32_e32 v83, v83
	v_rcp_f32_e32 v84, v84
	v_rcp_f32_e32 v85, v85
	v_pk_mul_f32 v[94:95], v[94:95], v[86:87]
	v_pk_mul_f32 v[96:97], v[96:97], v[88:89]
	v_pk_mul_f32 v[90:91], v[90:91], v[82:83]
	v_pk_mul_f32 v[92:93], v[92:93], v[84:85]
	v_cvt_pk_bf16_f32 v86, v94, v95
	v_cvt_pk_bf16_f32 v87, v96, v97
	v_cvt_pk_bf16_f32 v88, v90, v91
	v_cvt_pk_bf16_f32 v89, v92, v93
; __device__ __forceinline__ unsigned pk_bf16(float lo, float hi) { f32x2 v = {lo, hi}; bf16x2_t b = __builtin_convertvector(v, bf16x2_t); return __builtin_bit_cast(unsigned, b); }
; __device__ __forceinline__ float fast_exp2(float x) { return __builtin_amdgcn_exp2f(x); }
; __device__ __forceinline__ float fast_rcp(float x) { return __builtin_amdgcn_rcpf(x); }
;     __device__ __forceinline__ void operator()(const f32x4 (&acc)[2][2][4][2], const Unit& u, int wr, int wc, int fr, int fq, float rp0, float rp1, const f32x4& raw0, const f32x4& raw1, float& rn0, float& rn1) const {
;     ...
;             for (int m = 0; m < 4; ++m) {
;                 const int row = row0 + ai * HALF + m * 16; const float r = rs[ai * 4 + m];
;                 const float c1 = -1.4426950408889634f * r, r2 = r * r;
;                 const f32x4 ga = acc[ai][0][m][0], gb = acc[ai][0][m][1];
;                 const f32x4 ta = ga * c1, tb = gb * c1;
;                 f32x4 ea, eb;
; #pragma unroll
;                 for (int j = 0; j < 4; ++j) { ea[j] = fast_exp2(ta[j]); eb[j] = fast_exp2(tb[j]); }
;                 const f32x4 da = ea + 1.f, db = eb + 1.f;
;                 f32x4 qa, qb;
; #pragma unroll
;                 for (int j = 0; j < 4; ++j) { qa[j] = fast_rcp(da[j]); qb[j] = fast_rcp(db[j]); }
;                 const f32x4 oa = ((ga * acc[ai][1][m][0]) * r2) * qa, ob = ((gb * acc[ai][1][m][1]) * r2) * qb;
;                 u32x4 w;
;                 w.x = pk_bf16(oa[0], oa[1]); w.y = pk_bf16(oa[2], oa[3]); w.z = pk_bf16(ob[0], ob[1]); w.w = pk_bf16(ob[2], ob[3]);
;                 if (ai == 0 && m == 0) rstd_finish(raw0, raw1, rn0, rn1);
;                 *(u32x4*)(O + (size_t)row * FF + col0) = w;
	v_add_u32_e32 v170, 0x2c000, v161
	global_store_dwordx4 v170, v[86:89], s[24:25]
	v_mul_f32_e32 v228, 0xbfb8aa3b, v165
	v_pk_mul_f32 v[78:79], v[70:71], v[78:79]
	v_pk_mul_f32 v[80:81], v[72:73], v[80:81]
	v_pk_mul_f32 v[74:75], v[62:63], v[74:75]
	v_pk_mul_f32 v[76:77], v[64:65], v[76:77]
	v_pk_mul_f32 v[70:71], v[70:71], v[228:229] op_sel_hi:[1,0]
	v_pk_mul_f32 v[72:73], v[72:73], v[228:229] op_sel_hi:[1,0]
	v_pk_mul_f32 v[62:63], v[62:63], v[228:229] op_sel_hi:[1,0]
	v_pk_mul_f32 v[64:65], v[64:65], v[228:229] op_sel_hi:[1,0]
	v_exp_f32_e32 v70, v70
	v_exp_f32_e32 v71, v71
	v_exp_f32_e32 v72, v72
	v_exp_f32_e32 v73, v73
	v_exp_f32_e32 v62, v62
	v_exp_f32_e32 v63, v63
	v_exp_f32_e32 v64, v64
	v_exp_f32_e32 v65, v65
	v_pk_fma_f32 v[70:71], v[70:71], v[206:207], v[206:207] op_sel_hi:[1,0,0]
	v_pk_fma_f32 v[72:73], v[72:73], v[206:207], v[206:207] op_sel_hi:[1,0,0]
	v_pk_fma_f32 v[62:63], v[62:63], v[206:207], v[206:207] op_sel_hi:[1,0,0]
	v_pk_fma_f32 v[64:65], v[64:65], v[206:207], v[206:207] op_sel_hi:[1,0,0]
	v_rcp_f32_e32 v70, v70
	v_rcp_f32_e32 v71, v71
	v_rcp_f32_e32 v72, v72
	v_rcp_f32_e32 v73, v73
	v_rcp_f32_e32 v62, v62
	v_rcp_f32_e32 v63, v63
	v_rcp_f32_e32 v64, v64
	v_rcp_f32_e32 v65, v65
	v_pk_mul_f32 v[78:79], v[78:79], v[70:71]
	v_pk_mul_f32 v[80:81], v[80:81], v[72:73]
	v_pk_mul_f32 v[74:75], v[74:75], v[62:63]
	v_pk_mul_f32 v[76:77], v[76:77], v[64:65]
	v_cvt_pk_bf16_f32 v70, v78, v79
	v_cvt_pk_bf16_f32 v71, v80, v81
	v_cvt_pk_bf16_f32 v72, v74, v75
	v_cvt_pk_bf16_f32 v73, v76, v77
	v_add_u32_e32 v170, 0x42000, v161
	global_store_dwordx4 v170, v[70:73], s[24:25]
	v_mul_f32_e32 v228, 0xbfb8aa3b, v166
	v_pk_mul_f32 v[66:67], v[54:55], v[66:67]
	v_pk_mul_f32 v[68:69], v[56:57], v[68:69]
	v_pk_mul_f32 v[58:59], v[50:51], v[58:59]
	v_pk_mul_f32 v[60:61], v[52:53], v[60:61]
	v_pk_mul_f32 v[54:55], v[54:55], v[228:229] op_sel_hi:[1,0]
	v_pk_mul_f32 v[56:57], v[56:57], v[228:229] op_sel_hi:[1,0]
	v_pk_mul_f32 v[50:51], v[50:51], v[228:229] op_sel_hi:[1,0]
	v_pk_mul_f32 v[52:53], v[52:53], v[228:229] op_sel_hi:[1,0]
	v_exp_f32_e32 v54, v54
	v_exp_f32_e32 v55, v55
	v_exp_f32_e32 v56, v56
	v_exp_f32_e32 v57, v57
	v_exp_f32_e32 v50, v50
	v_exp_f32_e32 v51, v51
	v_exp_f32_e32 v52, v52
	v_exp_f32_e32 v53, v53
	v_pk_fma_f32 v[54:55], v[54:55], v[220:221], v[220:221] op_sel_hi:[1,0,0]
	v_pk_fma_f32 v[56:57], v[56:57], v[220:221], v[220:221] op_sel_hi:[1,0,0]
	v_pk_fma_f32 v[50:51], v[50:51], v[220:221], v[220:221] op_sel_hi:[1,0,0]
	v_pk_fma_f32 v[52:53], v[52:53], v[220:221], v[220:221] op_sel_hi:[1,0,0]
	v_rcp_f32_e32 v54, v54
	v_rcp_f32_e32 v55, v55
	v_rcp_f32_e32 v56, v56
	v_rcp_f32_e32 v57, v57
	v_rcp_f32_e32 v50, v50
	v_rcp_f32_e32 v51, v51
	v_rcp_f32_e32 v52, v52
	v_rcp_f32_e32 v53, v53
	v_pk_mul_f32 v[66:67], v[66:67], v[54:55]
	v_pk_mul_f32 v[68:69], v[68:69], v[56:57]
	v_pk_mul_f32 v[58:59], v[58:59], v[50:51]
	v_pk_mul_f32 v[60:61], v[60:61], v[52:53]
	v_cvt_pk_bf16_f32 v54, v66, v67
	v_cvt_pk_bf16_f32 v55, v68, v69
	v_cvt_pk_bf16_f32 v56, v58, v59
	v_cvt_pk_bf16_f32 v57, v60, v61
	v_add_u32_e32 v170, 0xb0000, v161
	global_store_dwordx4 v170, v[54:57], s[24:25]
	v_mul_f32_e32 v228, 0xbfb8aa3b, v167
	v_pk_mul_f32 v[46:47], v[38:39], v[46:47]
	v_pk_mul_f32 v[48:49], v[40:41], v[48:49]
	v_pk_mul_f32 v[42:43], v[34:35], v[42:43]
	v_pk_mul_f32 v[44:45], v[36:37], v[44:45]
	v_pk_mul_f32 v[38:39], v[38:39], v[228:229] op_sel_hi:[1,0]
	v_pk_mul_f32 v[40:41], v[40:41], v[228:229] op_sel_hi:[1,0]
	v_pk_mul_f32 v[34:35], v[34:35], v[228:229] op_sel_hi:[1,0]
	v_pk_mul_f32 v[36:37], v[36:37], v[228:229] op_sel_hi:[1,0]
	v_exp_f32_e32 v38, v38
	v_exp_f32_e32 v39, v39
	v_exp_f32_e32 v40, v40
	v_exp_f32_e32 v41, v41
	v_exp_f32_e32 v34, v34
	v_exp_f32_e32 v35, v35
	v_exp_f32_e32 v36, v36
	v_exp_f32_e32 v37, v37
	v_pk_fma_f32 v[38:39], v[38:39], v[222:223], v[222:223] op_sel_hi:[1,0,0]
	v_pk_fma_f32 v[40:41], v[40:41], v[222:223], v[222:223] op_sel_hi:[1,0,0]
	v_pk_fma_f32 v[34:35], v[34:35], v[222:223], v[222:223] op_sel_hi:[1,0,0]
	v_pk_fma_f32 v[36:37], v[36:37], v[222:223], v[222:223] op_sel_hi:[1,0,0]
	v_rcp_f32_e32 v38, v38
	v_rcp_f32_e32 v39, v39
	v_rcp_f32_e32 v40, v40
	v_rcp_f32_e32 v41, v41
	v_rcp_f32_e32 v34, v34
	v_rcp_f32_e32 v35, v35
	v_rcp_f32_e32 v36, v36
	v_rcp_f32_e32 v37, v37
	v_pk_mul_f32 v[46:47], v[46:47], v[38:39]
	v_pk_mul_f32 v[48:49], v[48:49], v[40:41]
; __device__ __forceinline__ unsigned pk_bf16(float lo, float hi) { f32x2 v = {lo, hi}; bf16x2_t b = __builtin_convertvector(v, bf16x2_t); return __builtin_bit_cast(unsigned, b); }
; __device__ __forceinline__ float fast_exp2(float x) { return __builtin_amdgcn_exp2f(x); }
; __device__ __forceinline__ float fast_rcp(float x) { return __builtin_amdgcn_rcpf(x); }
; __device__ __forceinline__ void rstd_finish(const f32x4& raw0, const f32x4& raw1, float& rn0, float& rn1) {
;     rn0 = rsqrtf(((raw0.x + raw0.y) + (raw0.z + raw0.w)) * (1.f / DM) + EPS); rn1 = rsqrtf(((raw1.x + raw1.y) + (raw1.z + raw1.w)) * (1.f / DM) + EPS);
;     asm volatile("" :: "v"(rn0), "v"(rn1) : "memory");
;     __device__ __forceinline__ void operator()(const f32x4 (&acc)[2][2][4][2], const Unit& u, int wr, int wc, int fr, int fq, float rp0, float rp1, const f32x4& raw0, const f32x4& raw1, float& rn0, float& rn1) const {
;     ...
;                 const int row = row0 + ai * HALF + m * 16; const float r = rs[ai * 4 + m];
;                 const float c1 = -1.4426950408889634f * r, r2 = r * r;
;                 const f32x4 ga = acc[ai][0][m][0], gb = acc[ai][0][m][1];
;                 const f32x4 ta = ga * c1, tb = gb * c1;
;                 f32x4 ea, eb;
; #pragma unroll
;                 for (int j = 0; j < 4; ++j) { ea[j] = fast_exp2(ta[j]); eb[j] = fast_exp2(tb[j]); }
;                 const f32x4 da = ea + 1.f, db = eb + 1.f;
;                 f32x4 qa, qb;
; #pragma unroll
;                 for (int j = 0; j < 4; ++j) { qa[j] = fast_rcp(da[j]); qb[j] = fast_rcp(db[j]); }
;                 const f32x4 oa = ((ga * acc[ai][1][m][0]) * r2) * qa, ob = ((gb * acc[ai][1][m][1]) * r2) * qb;
;                 u32x4 w;
;                 w.x = pk_bf16(oa[0], oa[1]); w.y = pk_bf16(oa[2], oa[3]); w.z = pk_bf16(ob[0], ob[1]); w.w = pk_bf16(ob[2], ob[3]);
;                 if (ai == 0 && m == 0) rstd_finish(raw0, raw1, rn0, rn1);
;                 *(u32x4*)(O + (size_t)row * FF + col0) = w;
	v_pk_mul_f32 v[42:43], v[42:43], v[34:35]
	v_pk_mul_f32 v[44:45], v[44:45], v[36:37]
	v_cvt_pk_bf16_f32 v38, v46, v47
	v_cvt_pk_bf16_f32 v39, v48, v49
	v_cvt_pk_bf16_f32 v40, v42, v43
	v_cvt_pk_bf16_f32 v41, v44, v45
	v_add_u32_e32 v170, 0xc6000, v161
	global_store_dwordx4 v170, v[38:41], s[24:25]
	v_mul_f32_e32 v228, 0xbfb8aa3b, v168
	v_pk_mul_f32 v[30:31], v[22:23], v[30:31]
	v_pk_mul_f32 v[32:33], v[24:25], v[32:33]
	v_pk_mul_f32 v[26:27], v[18:19], v[26:27]
	v_pk_mul_f32 v[28:29], v[20:21], v[28:29]
	v_pk_mul_f32 v[22:23], v[22:23], v[228:229] op_sel_hi:[1,0]
	v_pk_mul_f32 v[24:25], v[24:25], v[228:229] op_sel_hi:[1,0]
	v_pk_mul_f32 v[18:19], v[18:19], v[228:229] op_sel_hi:[1,0]
	v_pk_mul_f32 v[20:21], v[20:21], v[228:229] op_sel_hi:[1,0]
	v_exp_f32_e32 v22, v22
	v_exp_f32_e32 v23, v23
	v_exp_f32_e32 v24, v24
	v_exp_f32_e32 v25, v25
	v_exp_f32_e32 v18, v18
	v_exp_f32_e32 v19, v19
	v_exp_f32_e32 v20, v20
	v_exp_f32_e32 v21, v21
	v_pk_fma_f32 v[22:23], v[22:23], v[224:225], v[224:225] op_sel_hi:[1,0,0]
	v_pk_fma_f32 v[24:25], v[24:25], v[224:225], v[224:225] op_sel_hi:[1,0,0]
	v_pk_fma_f32 v[18:19], v[18:19], v[224:225], v[224:225] op_sel_hi:[1,0,0]
	v_pk_fma_f32 v[20:21], v[20:21], v[224:225], v[224:225] op_sel_hi:[1,0,0]
	v_rcp_f32_e32 v22, v22
	v_rcp_f32_e32 v23, v23
	v_rcp_f32_e32 v24, v24
	v_rcp_f32_e32 v25, v25
	v_rcp_f32_e32 v18, v18
	v_rcp_f32_e32 v19, v19
	v_rcp_f32_e32 v20, v20
	v_rcp_f32_e32 v21, v21
	v_pk_mul_f32 v[30:31], v[30:31], v[22:23]
	v_pk_mul_f32 v[32:33], v[32:33], v[24:25]
	v_pk_mul_f32 v[26:27], v[26:27], v[18:19]
	v_pk_mul_f32 v[28:29], v[28:29], v[20:21]
	v_cvt_pk_bf16_f32 v22, v30, v31
	v_cvt_pk_bf16_f32 v23, v32, v33
	v_cvt_pk_bf16_f32 v24, v26, v27
	v_cvt_pk_bf16_f32 v25, v28, v29
	v_add_u32_e32 v170, 0xdc000, v161
	global_store_dwordx4 v170, v[22:25], s[24:25]
	v_mul_f32_e32 v228, 0xbfb8aa3b, v169
	v_pk_mul_f32 v[14:15], v[6:7], v[14:15]
	v_pk_mul_f32 v[16:17], v[8:9], v[16:17]
	v_pk_mul_f32 v[10:11], v[2:3], v[10:11]
	v_pk_mul_f32 v[12:13], v[4:5], v[12:13]
	v_pk_mul_f32 v[6:7], v[6:7], v[228:229] op_sel_hi:[1,0]
	v_pk_mul_f32 v[8:9], v[8:9], v[228:229] op_sel_hi:[1,0]
	v_pk_mul_f32 v[2:3], v[2:3], v[228:229] op_sel_hi:[1,0]
	v_pk_mul_f32 v[4:5], v[4:5], v[228:229] op_sel_hi:[1,0]
	v_exp_f32_e32 v6, v6
	v_exp_f32_e32 v7, v7
	v_exp_f32_e32 v8, v8
	v_exp_f32_e32 v9, v9
	v_exp_f32_e32 v2, v2
	v_exp_f32_e32 v3, v3
	v_exp_f32_e32 v4, v4
	v_exp_f32_e32 v5, v5
	v_pk_fma_f32 v[6:7], v[6:7], v[226:227], v[226:227] op_sel_hi:[1,0,0]
	v_pk_fma_f32 v[8:9], v[8:9], v[226:227], v[226:227] op_sel_hi:[1,0,0]
	v_pk_fma_f32 v[2:3], v[2:3], v[226:227], v[226:227] op_sel_hi:[1,0,0]
	v_pk_fma_f32 v[4:5], v[4:5], v[226:227], v[226:227] op_sel_hi:[1,0,0]
	v_rcp_f32_e32 v6, v6
	v_rcp_f32_e32 v7, v7
	v_rcp_f32_e32 v8, v8
	v_rcp_f32_e32 v9, v9
	v_rcp_f32_e32 v2, v2
	v_rcp_f32_e32 v3, v3
	v_rcp_f32_e32 v4, v4
	v_rcp_f32_e32 v5, v5
	v_pk_mul_f32 v[14:15], v[14:15], v[6:7]
	v_pk_mul_f32 v[16:17], v[16:17], v[8:9]
	v_pk_mul_f32 v[10:11], v[10:11], v[2:3]
	v_pk_mul_f32 v[12:13], v[12:13], v[4:5]
	v_cvt_pk_bf16_f32 v6, v14, v15
	v_cvt_pk_bf16_f32 v7, v16, v17
	v_cvt_pk_bf16_f32 v8, v10, v11
	v_cvt_pk_bf16_f32 v9, v12, v13
	v_add_u32_e32 v170, 0xf2000, v161
	global_store_dwordx4 v170, v[6:9], s[24:25]
	s_waitcnt vmcnt(8)
	v_mov_b32_e32 v122, v135
	v_mov_b32_e32 v123, v136
	v_mov_b32_e32 v135, v137
	v_mov_b32_e32 v124, v131
	v_mov_b32_e32 v125, v132
	v_mov_b32_e32 v131, v133
	v_pk_add_f32 v[122:123], v[122:123], v[134:135]
	v_pk_add_f32 v[124:125], v[124:125], v[130:131]
	v_mov_b32_e32 v126, v124
	v_mov_b32_e32 v127, v122
	v_mov_b32_e32 v122, v125
	v_pk_add_f32 v[122:123], v[126:127], v[122:123]
	v_pk_fma_f32 v[122:123], v[122:123], s[84:85], v[182:183] op_sel_hi:[1,0,0]
	v_mov_b32_e32 v252, v122
	v_mov_b32_e32 v253, v123
	v_mul_f32_e32 v119, 0x4b800000, v123
	v_mul_f32_e32 v118, 0x4b800000, v122
	v_cmp_gt_f32_e64 s[100:101], s89, v123
	v_cmp_gt_f32_e64 s[6:7], s89, v122
	s_nop 1
	v_cndmask_b32_e64 v119, v123, v119, s[100:101]
	v_cndmask_b32_e64 v118, v122, v118, s[6:7]
	v_rsq_f32_e32 v123, v119
	v_rsq_f32_e32 v122, v118
	s_nop 0
	v_pk_mul_f32 v[120:121], v[122:123], s[78:79] op_sel_hi:[1,0]
	v_cndmask_b32_e64 v145, v123, v121, s[100:101]
	v_cndmask_b32_e64 v144, v122, v120, s[6:7]
	s_cbranch_vccnz .LBB0_315
	s_andn2_b64 vcc, exec, s[2:3]
	s_cbranch_vccnz .LBB0_314
	s_barrier
	s_branch .LBB0_314
